# LRU ping-pong: wave groups 0-3/4-7 staggered by half an iteration (group-local IO tiles, bwd wave flip, double-buffered scan aggregates)
# speedup vs baseline: 1.0085x; 1.0059x over previous
; #define LAS __attribute__((address_space(3)))
; __device__ __forceinline__ int opaque_tid() { int t = threadIdx.x; asm volatile("" : "+v"(t)); return t; }
; #define LDS_BARRIER() do { asm volatile("s_waitcnt lgkmcnt(0)" ::: "memory"); __builtin_amdgcn_s_barrier(); asm volatile("" ::: "memory"); } while (0)
; __device__ __forceinline__ void lru_strip(LAS unsigned char* lds, const Params& P, int strip, bool dry) {
;     const int tid = opaque_tid();
;     const int b = strip >> 5, h = (strip >> 2) & 7, q = strip & 3;
;     LAS float* CWL = (LAS float*)(lds + 256 * XC_PITCH + 2048 + 64 * XC_PITCH);
;     for (int i = tid; i < 640; i += NTHREADS) { const int k = i >> 7, c = i & 127; CWL[i] = k < 4 ? P.conv_w[k * 1024 + h * 128 + c] : P.conv_b[h * 128 + c]; }
;     LDS_BARRIER();
; __global__ void __launch_bounds__(NTHREADS, 2) fwd_megakernel(Params P) {
;     ...
;         for (int s2 = bx; s2 < 256; s2 += G) { lru_strip(lds, P, ((s2 & 7) << 5) | (s2 >> 3), false); __syncthreads(); }
.LBB0_277:
	s_cmp_lg_u32 s101, 0
	s_cbranch_scc1 .Lpp_b_noy
	s_barrier

; template <int dir>
; __device__ __forceinline__ void lru_pass(LAS unsigned char* lds, const Params& P, int b, int h, int q, bool dry) {
;     const int tid = opaque_tid(), lane = tid & 63, wid = __builtin_amdgcn_readfirstlane(tid >> 6), g = lane >> 5, nl = lane & 31;
;     const int chl = q * 32 + nl, ch = h * 128 + chl;
;     LAS unsigned char* XC = lds;
;     LAS float* AGG = (LAS float*)(lds + 256 * XC_PITCH);
;     LAS unsigned char* WB = lds + 256 * XC_PITCH + 2048;
;     LAS float* CWL = (LAS float*)(lds + 256 * XC_PITCH + 2048 + 64 * XC_PITCH);
;     LAS unsigned char* TIN = lds + LRU_IO_OFF;
;     LAS unsigned char* TOUT = lds + LRU_IO_OFF + 256 * (dir == 0 ? IO_NP : IO_WP);
;     bf16_t* Z = (bf16_t*)(P.ws + WS_Z); const bf16_t* ZC = (const bf16_t*)(P.ws + WS_ZC); unsigned* HFW = (unsigned*)(P.ws + WS_HF);
;     const bf16_t* LruW = (const bf16_t*)(P.ws + WS_LRUW);
;     const int cgp = tid & 15, tr = tid >> 4;
;     const int s_i = 16 * ((nl >> 2) & 1) + ((nl >> 3) << 2) + (nl & 3);
;     const bf16_t* Zg = Z + ZSLAB(8 + h, (size_t)b * SEQ) + q * 32;
;     unsigned* Hg = HFW + (size_t)b * SEQ * DM + h * 128 + q * 32;
;     {
; #pragma unroll
;         for (int i = 0; i < 2; ++i) { const int idx = tid + i * NTHREADS, gate = idx >> 9, n = (idx >> 4) & 31, kc = idx & 15;
;             *(LAS u32x4*)(WB + (gate * 32 + n) * XC_PITCH + kc * 16) = *(const u32x4*)(LruW + ((size_t)((dir * 2 + gate) * 8 + h) * 128 + q * 32 + n) * 128 + kc * 8); }
;         const float br = -LOG2E * P.lru_ba[(dir * 8 + h) * 128 + chl], bi = -LOG2E * P.lru_bx[(dir * 8 + h) * 128 + chl];
;         const float lam = P.lru_lambda[dir * 1024 + ch];
;         const float cl = -8.0f * LOG2E * log1pf(__expf(-lam));
;         float carry = 0.f;
;         LruTile cur = lru_tile(Z, ZC, b, h, dir, 0);
;         u32x4 rows[11];
;         constexpr int NIN = dir == 0 ? 2 : 4;
;         u32x4 inr[NIN];
; __device__ __forceinline__ void lru_strip(LAS unsigned char* lds, const Params& P, int strip, bool dry) {
;     const int tid = opaque_tid();
;     const int b = strip >> 5, h = (strip >> 2) & 7, q = strip & 3;
;     LAS float* CWL = (LAS float*)(lds + 256 * XC_PITCH + 2048 + 64 * XC_PITCH);
;     for (int i = tid; i < 640; i += NTHREADS) { const int k = i >> 7, c = i & 127; CWL[i] = k < 4 ? P.conv_w[k * 1024 + h * 128 + c] : P.conv_b[h * 128 + c]; }
.LBB0_278:
	s_ashr_i32 s25, s2, 3
	v_mov_b32_e32 v128, v167
	s_bfe_u32 s26, s25, 0x30002
	s_lshl_b32 s27, s26, 7
	v_and_b32_e32 v204, 0x7f, v128
	v_or_b32_e32 v204, s27, v204
	v_lshrrev_b32_e32 v205, 7, v128
	v_lshl_or_b32 v205, v205, 10, v204
	v_lshlrev_b32_e32 v205, 2, v205
	v_lshlrev_b32_e32 v204, 2, v204
	global_load_dword v205, v205, s[52:53]
	global_load_dword v204, v204, s[54:55]
	v_readlane_b32 s0, v255, 19
	s_nop 3
	v_lshl_add_u32 v206, v128, 2, s0
	v_mov_b32_e32 v12, v167
	s_lshl_b32 s0, s25, 5
	s_and_b32 s28, s0, 0x60
	v_and_b32_e32 v15, 31, v12
	v_or_b32_e32 v17, s28, v15
	v_add_u32_e32 v14, 0x200, v12
	v_or_b32_e32 v11, s27, v17
	v_ashrrev_i32_e32 v8, 9, v12
	v_ashrrev_i32_e32 v10, 9, v14
	v_lshlrev_b32_e32 v16, 2, v11
	v_and_b32_e32 v13, 15, v12
	v_lshl_or_b32 v2, v8, 3, s26
	v_lshl_or_b32 v6, v10, 3, s26
	global_load_dword v18, v16, s[64:65]
	v_bfe_u32 v9, v12, 4, 5
	v_lshlrev_b32_e32 v64, 4, v13
	v_ashrrev_i32_e32 v3, 31, v2
	v_ashrrev_i32_e32 v7, 31, v6
	v_or_b32_e32 v4, s28, v9
	v_lshl_add_u64 v[0:1], s[38:39], 0, v[64:65]
	v_lshlrev_b64 v[2:3], 15, v[2:3]
	v_lshlrev_b64 v[6:7], 15, v[6:7]
	v_lshlrev_b32_e32 v4, 8, v4
	v_mov_b32_e32 v5, v65
	v_lshl_add_u64 v[2:3], v[0:1], 0, v[2:3]
	v_lshl_add_u64 v[0:1], v[0:1], 0, v[6:7]
	v_lshl_add_u64 v[2:3], v[2:3], 0, v[4:5]
	v_lshl_add_u64 v[4:5], v[0:1], 0, v[4:5]
	global_load_dwordx4 v[0:3], v[2:3], off
	s_nop 0
	global_load_dwordx4 v[4:7], v[4:5], off
	v_lshlrev_b32_e32 v11, 2, v12
	v_lshl_or_b32 v21, v8, 5, v9
	v_add_u32_e32 v8, s88, v64
	v_lshl_or_b32 v9, v10, 5, v9
	v_and_b32_e32 v22, 16, v11
	v_mad_u64_u32 v[10:11], s[4:5], v21, s89, v[8:9]
	v_mad_u64_u32 v[8:9], s[4:5], v9, s89, v[8:9]
	global_load_dword v9, v16, s[58:59]
	global_load_dword v11, v16, s[62:63]
	s_lshl_b32 s0, s2, 5
	s_and_b32 s0, s0, 0xe0
	s_or_b32 s1, s0, s25
	s_ashr_i32 s78, s1, 5
	s_ashr_i32 s79, s78, 31
	s_lshl_b32 s20, s26, 22
	s_lshl_b64 s[18:19], s[78:79], 19
	s_lshl_b64 s[44:45], s[78:79], 23
	v_readlane_b32 s1, v255, 18
	s_add_u32 s1, s1, s44
	s_addc_u32 s4, s33, s45
	s_lshl_b32 s5, s27, 2
	s_add_u32 s1, s1, s5
	s_addc_u32 s4, s4, 0
	s_add_u32 s5, s68, s18
	s_addc_u32 s6, s69, s19
	s_lshl_b32 s7, s27, 1
	s_add_u32 s48, s5, s7
	s_addc_u32 s49, s6, 0
	s_add_u32 s50, s48, 0x1000
	s_addc_u32 s51, s49, 0
	s_add_u32 s56, s48, 0x1800
	s_addc_u32 s57, s49, 0
	s_add_u32 s60, s48, 0x2000
	s_addc_u32 s61, s49, 0
	s_add_u32 s66, s48, 0x2800
	s_addc_u32 s67, s49, 0
	s_add_u32 s70, s48, 0x3000
	s_addc_u32 s71, s49, 0
	v_ashrrev_i32_e32 v36, 4, v12
	v_lshlrev_b32_e32 v37, 3, v13
	s_add_u32 s72, s48, 0x3800
	s_addc_u32 s73, s49, 0
	s_add_u32 s74, s48, 0x4000
	s_addc_u32 s75, s49, 0
	s_add_u32 s76, s48, 0x4800
	s_addc_u32 s77, s49, 0
	v_readfirstlane_b32 s0, v12
	s_ashr_i32 s6, s0, 6
	s_lshl_b32 s5, s28, 2
	s_add_u32 s8, s1, s5
	v_bfe_u32 v19, v12, 5, 1
	v_lshrrev_b32_e32 v20, 1, v12
	v_and_b32_e32 v33, 3, v12
	s_addc_u32 s9, s4, 0
	v_lshl_or_b32 v110, v36, 13, v37
	v_mov_b32_e32 v111, v65
	v_lshlrev_b64 v[110:111], 1, v[110:111]
	v_lshl_add_u64 v[108:109], s[48:49], 0, v[110:111]
	global_load_dwordx4 v[68:71], v[108:109], off offset:-2048
	global_load_dwordx4 v[72:75], v[108:109], off
	global_load_dwordx4 v[76:79], v[108:109], off offset:2048
	v_lshl_add_u64 v[108:109], s[50:51], 0, v[110:111]
	global_load_dwordx4 v[80:83], v[108:109], off
	v_lshl_add_u64 v[108:109], s[56:57], 0, v[110:111]
	global_load_dwordx4 v[84:87], v[108:109], off
	v_lshl_add_u64 v[108:109], s[60:61], 0, v[110:111]
	global_load_dwordx4 v[88:91], v[108:109], off
	v_lshl_add_u64 v[108:109], s[66:67], 0, v[110:111]
	global_load_dwordx4 v[92:95], v[108:109], off
	v_lshl_add_u64 v[108:109], s[70:71], 0, v[110:111]
	global_load_dwordx4 v[96:99], v[108:109], off
	v_lshl_add_u64 v[108:109], s[72:73], 0, v[110:111]
	global_load_dwordx4 v[100:103], v[108:109], off
	v_lshl_add_u64 v[108:109], s[74:75], 0, v[110:111]
	global_load_dwordx4 v[104:107], v[108:109], off
	v_lshl_add_u64 v[108:109], s[76:77], 0, v[110:111]
	global_load_dwordx4 v[108:111], v[108:109], off
	s_waitcnt vmcnt(14)
	ds_write_b128 v10, v[0:3]
	s_waitcnt vmcnt(13)
	ds_write_b128 v8, v[4:7]
	ds_write_b32 v206, v205
	v_cmp_gt_u32_e32 vcc, 0x80, v128
	s_and_saveexec_b64 s[14:15], vcc
	ds_write_b32 v206, v204 offset:2048
	s_or_b64 exec, exec, s[14:15]
	v_mul_f32_e32 v16, 0xbfb8aa3b, v18
	v_exp_f32_e32 v16, v16
	s_lshl_b32 s1, s6, 5
	s_and_b32 s0, s0, 0x3fffffc0
	v_add_u32_e32 v39, 0, v64
	v_add_f32_e32 v2, 1.0, v16
	v_add_f32_e32 v3, -1.0, v2
	v_frexp_mant_f32_e32 v4, v2
	v_cvt_f64_f32_e32 v[0:1], v2
	v_sub_f32_e32 v5, v3, v2
	v_frexp_exp_i32_f64_e32 v0, v[0:1]
	v_cmp_gt_f32_e32 vcc, s80, v4
	v_sub_f32_e32 v3, v16, v3
	v_add_f32_e32 v1, 1.0, v5
	v_subbrev_co_u32_e32 v0, vcc, 0, v0, vcc
	v_add_f32_e32 v1, v3, v1
	v_sub_u32_e32 v3, 0, v0
	v_ldexp_f32 v2, v2, v3
	v_ldexp_f32 v1, v1, v3
	v_add_f32_e32 v3, -1.0, v2
	v_add_f32_e32 v4, 1.0, v2
	v_add_f32_e32 v5, 1.0, v3
	v_add_f32_e32 v6, -1.0, v4
	v_sub_f32_e32 v5, v2, v5
	v_sub_f32_e32 v2, v2, v6
	v_add_f32_e32 v5, v1, v5
	v_add_f32_e32 v1, v1, v2
	v_add_f32_e32 v6, v4, v1
	v_rcp_f32_e32 v7, v6
	v_add_f32_e32 v2, v3, v5
	v_sub_f32_e32 v4, v6, v4
	v_sub_f32_e32 v3, v2, v3
	v_sub_f32_e32 v1, v1, v4
	v_mul_f32_e32 v4, v2, v7
	v_sub_f32_e32 v3, v5, v3
	v_mul_f32_e32 v5, v6, v4
	v_fma_f32 v8, v4, v6, -v5
	v_fmac_f32_e32 v8, v4, v1
	v_add_f32_e32 v10, v5, v8
	v_sub_f32_e32 v18, v2, v10
	v_sub_f32_e32 v2, v2, v18
	v_sub_f32_e32 v5, v10, v5
	v_sub_f32_e32 v2, v2, v10
	v_sub_f32_e32 v5, v5, v8
	v_add_f32_e32 v2, v3, v2
	v_add_f32_e32 v2, v5, v2
	v_add_f32_e32 v3, v18, v2
	v_mul_f32_e32 v5, v7, v3
	v_mul_f32_e32 v10, v6, v5
	v_fma_f32 v6, v5, v6, -v10
; template <int dir>
; __device__ __forceinline__ void lru_pass(LAS unsigned char* lds, const Params& P, int b, int h, int q, bool dry) {
;     ...
;         const float br = -LOG2E * P.lru_ba[(dir * 8 + h) * 128 + chl], bi = -LOG2E * P.lru_bx[(dir * 8 + h) * 128 + chl];
;         const float lam = P.lru_lambda[dir * 1024 + ch];
;         const float cl = -8.0f * LOG2E * log1pf(__expf(-lam));
;         float carry = 0.f;
;         LruTile cur = lru_tile(Z, ZC, b, h, dir, 0);
;         u32x4 rows[11];
;         constexpr int NIN = dir == 0 ? 2 : 4;
;         u32x4 inr[NIN];
;         lru_load_rows(rows, cur, tr, cgp);
; #pragma unroll
;         for (int i = 0; i < NIN; ++i) inr[i] = (u32x4){0u, 0u, 0u, 0u};
;         int t0_prev = 0;
	v_fmac_f32_e32 v6, v5, v1
	v_add_f32_e32 v1, v10, v6
	v_sub_f32_e32 v8, v18, v3
	v_sub_f32_e32 v18, v3, v1
	v_sub_f32_e32 v3, v3, v18
	v_add_f32_e32 v2, v2, v8
	v_sub_f32_e32 v10, v1, v10
	v_sub_f32_e32 v1, v3, v1
	v_sub_f32_e32 v6, v10, v6
	v_add_f32_e32 v1, v2, v1
	v_cvt_f32_i32_e32 v0, v0
	v_add_f32_e32 v8, v4, v5
	v_add_f32_e32 v1, v6, v1
	v_add_f32_e32 v1, v18, v1
	v_sub_f32_e32 v2, v8, v4
	v_mul_f32_e32 v1, v7, v1
	v_sub_f32_e32 v2, v5, v2
	v_add_f32_e32 v1, v2, v1
	v_mul_f32_e32 v5, 0x3f317218, v0
	v_add_f32_e32 v2, v8, v1
	v_fma_f32 v6, v0, s81, -v5
	v_fmac_f32_e32 v6, 0xb102e308, v0
	v_sub_f32_e32 v0, v2, v8
	v_mul_f32_e32 v3, v2, v2
	v_sub_f32_e32 v0, v1, v0
	v_add_f32_e32 v1, v5, v6
	v_fmamk_f32 v4, v3, 0x3e9b6dac, v200
	v_sub_f32_e32 v5, v1, v5
	v_fmaak_f32 v4, v3, v4, 0x3f2aaada
	v_sub_f32_e32 v5, v6, v5
	v_ldexp_f32 v6, v2, 1
	v_mul_f32_e32 v2, v2, v3
	v_mul_f32_e32 v2, v2, v4
	v_add_f32_e32 v3, v6, v2
	v_sub_f32_e32 v4, v3, v6
	v_ldexp_f32 v0, v0, 1
	v_sub_f32_e32 v2, v2, v4
	v_add_f32_e32 v0, v0, v2
	v_add_f32_e32 v2, v3, v0
	v_sub_f32_e32 v3, v2, v3
	v_sub_f32_e32 v0, v0, v3
	v_add_f32_e32 v3, v1, v2
	v_sub_f32_e32 v4, v3, v1
	v_sub_f32_e32 v6, v3, v4
	v_sub_f32_e32 v1, v1, v6
	v_sub_f32_e32 v2, v2, v4
	v_add_f32_e32 v1, v2, v1
	v_add_f32_e32 v2, v5, v0
	v_sub_f32_e32 v4, v2, v5
	v_add_f32_e32 v1, v2, v1
	v_sub_f32_e32 v6, v2, v4
	v_add_f32_e32 v2, v3, v1
	v_sub_f32_e32 v5, v5, v6
	v_sub_f32_e32 v0, v0, v4
	v_sub_f32_e32 v3, v2, v3
	v_add_f32_e32 v0, v0, v5
	v_sub_f32_e32 v1, v1, v3
	v_add_f32_e32 v0, v0, v1
	v_add_f32_e32 v0, v2, v0
	v_cmp_neq_f32_e32 vcc, s91, v16
	v_mov_b32_e32 v1, v65
	v_lshlrev_b32_e32 v41, 4, v19
	v_cndmask_b32_e32 v0, v201, v0, vcc
	v_cmp_ngt_f32_e32 vcc, -1.0, v16
	s_cmp_eq_u32 s6, 7
	v_or_b32_e32 v35, s1, v41
	v_cndmask_b32_e32 v0, v202, v0, vcc
	v_cmp_neq_f32_e32 vcc, -1.0, v16
	v_ashrrev_i32_e32 v32, 2, v12
	v_ashrrev_i32_e32 v34, 2, v14
	v_cndmask_b32_e32 v0, v203, v0, vcc
	v_cmp_lt_f32_e64 vcc, |v16|, s92
	v_lshlrev_b32_e32 v53, 4, v33
	v_mul_lo_u32 v48, v32, s87
	v_cndmask_b32_e32 v6, v0, v16, vcc
	v_lshlrev_b32_e32 v1, 2, v15
	v_lshlrev_b32_e32 v2, 4, v12
	v_add_u32_e32 v140, s94, v1
	v_and_b32_e32 v3, 48, v2
	v_and_b32_e32 v64, 0x70, v2
	v_and_or_b32 v2, v20, 12, v33
	v_or3_b32 v2, v2, v22, s1
	v_lshl_add_u32 v147, s0, 2, v140
	s_cselect_b64 s[0:1], -1, 0
	s_cmp_eq_u32 s6, 6
	s_cselect_b64 s[16:17], -1, 0
	s_cmp_eq_u32 s6, 5
	s_cselect_b64 s[4:5], -1, 0
	s_cmp_eq_u32 s6, 4
	v_lshl_add_u64 v[130:131], s[8:9], 0, v[64:65]
	s_cselect_b64 s[8:9], -1, 0
	s_cmp_eq_u32 s6, 3
	s_cselect_b64 s[10:11], -1, 0
	s_cmp_eq_u32 s6, 2
	s_cselect_b64 s[12:13], -1, 0
	s_cmp_eq_u32 s6, 1
	s_cselect_b64 s[14:15], -1, 0
	s_add_u32 s46, s20, s18
	s_addc_u32 s47, 0, s19
	s_lshl_b32 s6, s2, 3
	v_ashrrev_i32_e32 v33, 31, v32
	v_mul_lo_u32 v50, v35, s89
	v_mul_lo_u32 v51, v35, s87
	v_mul_lo_u32 v52, v35, s30
	v_ashrrev_i32_e32 v35, 31, v34
	s_bfe_u32 s29, s2, 0x20003
	s_and_b32 s6, s6, 0xc0
	v_lshlrev_b64 v[32:33], 8, v[32:33]
	v_mul_lo_u32 v2, v2, s89
	v_add_u32_e32 v46, s96, v1
	v_mul_lo_u32 v49, v34, s87
	v_add_u32_e32 v1, 0x400, v12
	v_lshlrev_b64 v[34:35], 8, v[34:35]
	v_lshl_add_u64 v[32:33], s[46:47], 0, v[32:33]
	s_add_u32 s18, s82, s46
	v_lshlrev_b32_e32 v38, 5, v13
	v_add_u32_e32 v129, s96, v64
	v_add_u32_e32 v42, 0, v2
	v_mov_b32_e32 v2, s88
	v_ashrrev_i32_e32 v143, 3, v1
	v_add_u32_e32 v1, 0x600, v12
	v_lshl_add_u64 v[34:35], s[46:47], 0, v[34:35]
	v_or3_b32 v32, v32, s6, v53
	v_lshl_or_b32 v64, v36, 10, v37
	s_addc_u32 s19, s83, s47
	v_mov_b32_e32 v66, v65
	v_mov_b32_e32 v67, v65
	s_waitcnt vmcnt(12)
	v_mul_f32_e32 v0, 0xbfb8aa3b, v9
	s_waitcnt vmcnt(11)
	v_mul_f32_e32 v16, 0xbfb8aa3b, v11
	v_add_u32_e32 v40, s95, v3
	v_mad_u32_u24 v43, v15, s89, v2
	v_lshl_add_u32 v44, v17, 1, 0
	v_lshl_add_u32 v45, v15, 1, s95
	v_mul_lo_u32 v47, v36, s93
	v_ashrrev_i32_e32 v148, 3, v12
	v_ashrrev_i32_e32 v145, 3, v14
	v_ashrrev_i32_e32 v141, 3, v1
	v_or3_b32 v34, v34, s6, v53
	v_lshl_add_u64 v[134:135], s[40:41], 0, v[32:33]
	v_lshl_add_u64 v[136:137], v[64:65], 1, s[18:19]
	v_mov_b32_e32 v64, v65
	v_add_u32_e32 v32, 0, v38
	v_mov_b64_e32 v[114:115], v[66:67]
	v_mov_b64_e32 v[118:119], v[66:67]
	s_mov_b32 s90, 0
	v_mul_f32_e32 v138, 0xc138aa3b, v6
	v_lshl_add_u32 v139, v36, 3, -1
	v_cmp_eq_u32_e32 vcc, 0, v19
	v_mul_lo_u32 v149, v148, s30
	v_mul_lo_u32 v146, v145, s30
	v_mul_lo_u32 v144, v143, s30
	v_mul_lo_u32 v142, v141, s30
	v_mov_b32_e32 v1, v0
	v_mov_b32_e32 v2, v0
	v_mov_b32_e32 v3, v0
	v_mov_b32_e32 v4, v0
	v_mov_b32_e32 v5, v0
	v_mov_b32_e32 v6, v0
	v_mov_b32_e32 v7, v0
	v_mov_b32_e32 v8, v0
	v_mov_b32_e32 v9, v0
	v_mov_b32_e32 v10, v0
	v_mov_b32_e32 v11, v0
	v_mov_b32_e32 v12, v0
	v_mov_b32_e32 v13, v0
	v_mov_b32_e32 v14, v0
	v_mov_b32_e32 v15, v0
	v_mov_b32_e32 v17, v16
	v_mov_b32_e32 v18, v16
	v_mov_b32_e32 v19, v16
	v_mov_b32_e32 v20, v16
	v_mov_b32_e32 v21, v16
	v_mov_b32_e32 v22, v16
	v_mov_b32_e32 v23, v16
	v_mov_b32_e32 v24, v16
	v_mov_b32_e32 v25, v16
	v_mov_b32_e32 v26, v16
	v_mov_b32_e32 v27, v16
	v_mov_b32_e32 v28, v16
	v_mov_b32_e32 v29, v16
	v_mov_b32_e32 v30, v16
	v_mov_b32_e32 v31, v16
	v_lshl_add_u64 v[132:133], s[40:41], 0, v[34:35]
	s_movk_i32 s92, 0x100
	v_mov_b32_e32 v165, 0
	s_mov_b64 s[80:81], 0
	v_add_u32_e32 v150, 0x15c00, v32
	v_add_u32_e32 v151, v39, v47
	v_add_u32_e32 v158, v40, v48
	v_add_u32_e32 v159, v40, v49
	v_add_u32_e32 v160, v42, v41
	v_add_u32_e32 v161, v43, v41
	v_add_u32_e32 v162, v44, v50
	v_add_u32_e32 v163, v45, v51
	v_add_u32_e32 v164, v46, v52
	v_mov_b64_e32 v[112:113], v[64:65]
	v_mov_b64_e32 v[116:117], v[64:65]
	s_mov_b32 s91, 0
	s_mov_b32 s93, 0
	s_mov_b32 s97, 0
; #define LDS_BARRIER() do { asm volatile("s_waitcnt lgkmcnt(0)" ::: "memory"); __builtin_amdgcn_s_barrier(); asm volatile("" ::: "memory"); } while (0)
; template <int dir>
; __device__ __forceinline__ void lru_pass(LAS unsigned char* lds, const Params& P, int b, int h, int q, bool dry) {
;     ...
;             const float Po = __shfl_xor(Pp, 32), Eo = __shfl_xor(E, 32);
;             const float P0 = g ? Po : Pp, E0 = g ? Eo : E, P1 = g ? Pp : Po, E1 = g ? E : Eo;
;             if (g == 0) { AGG[(wid * 2 + 0) * 32 + nl] = P0 * P1; AGG[(wid * 2 + 1) * 32 + nl] = fmaf(P1, E0, E1); }
;             LDS_BARRIER();
;             float cin = carry, cend = carry;
; #pragma unroll
;             for (int w = 0; w < 8; ++w) { const float pw = AGG[(w * 2 + 0) * 32 + nl], ew = AGG[(w * 2 + 1) * 32 + nl]; if (w == wid) cin = cend; cend = fmaf(pw, cend, ew); }
	v_lshrrev_b32_e32 v254, 8, v167
	v_mul_u32_u24_e32 v252, 0x1400, v254
	v_add_u32_e32 v158, v158, v252
	v_add_u32_e32 v159, v159, v252
	v_add_u32_e32 v159, 0xffffec00, v159
	v_lshlrev_b32_e32 v252, 14, v254
	v_mov_b32_e32 v253, 0
	v_lshl_add_u64 v[134:135], v[252:253], 0, v[134:135]
	v_lshl_add_u64 v[132:133], v[252:253], 0, v[132:133]
	s_mov_b32 s18, 0xffffc000
	s_mov_b32 s19, -1
	v_lshl_add_u64 v[132:133], v[132:133], 0, s[18:19]
	v_mul_u32_u24_e32 v252, 0x3600, v254
	v_add_u32_e32 v149, v149, v252
	v_add_u32_e32 v146, v146, v252
	v_add_u32_e32 v144, v144, v252
	v_add_u32_e32 v142, v142, v252
	v_add_u32_e32 v146, 0xffffee00, v146
	v_add_u32_e32 v144, 0xffffdc00, v144
	v_add_u32_e32 v142, 0xffffca00, v142
	v_mul_u32_u24_e32 v252, 0x60, v254
	v_add_u32_e32 v148, v148, v252
	v_add_u32_e32 v145, v145, v252
	v_add_u32_e32 v143, v143, v252
	v_add_u32_e32 v141, v141, v252
	v_add_u32_e32 v145, 0xffffffe0, v145
	v_add_u32_e32 v143, 0xffffffc0, v143
	v_add_u32_e32 v141, 0xffffffa0, v141
	v_lshrrev_b32_e32 v253, 6, v167
	s_nop 1
	v_readfirstlane_b32 s18, v253
	s_lshr_b32 s101, s18, 2
	s_or_b32 s19, s18, 4
	s_cmp_eq_u32 s19, 7
	s_cselect_b64 s[0:1], -1, 0
	s_cmp_eq_u32 s19, 6
	s_cselect_b64 s[16:17], -1, 0
	s_cmp_eq_u32 s19, 5
	s_cselect_b64 s[4:5], -1, 0
	s_cmp_eq_u32 s19, 4
	s_cselect_b64 s[8:9], -1, 0
	s_mov_b64 s[10:11], 0
	s_mov_b64 s[12:13], 0
	s_mov_b64 s[14:15], 0
	s_mov_b32 s98, 0
	s_cmp_eq_u32 s101, 0
	s_cselect_b32 s99, 0x14400, 0
	s_cselect_b32 s100, 0, 0x400
	v_add_u32_e32 v253, 0x14000, v147
	v_mov_b32_e32 v254, 1.0
	v_mov_b32_e32 v252, 0
	ds_write2_b32 v253, v254, v252 offset1:32
	s_waitcnt lgkmcnt(0)
	s_barrier
	s_cmp_eq_u32 s101, 0
	s_cbranch_scc1 .Lpp_f_nox
	s_barrier
.Lpp_f_nox:
.LBB0_292:
	v_add_u32_e32 v32, s97, v139
	v_cmp_lt_i32_e64 s[18:19], -1, v32
	v_cmp_gt_i32_e64 s[20:21], s92, v32
	s_and_b64 s[18:19], s[18:19], s[20:21]
	v_add_u32_e32 v33, 9, v32
	s_waitcnt vmcnt(10)
	v_cndmask_b32_e64 v71, 0, v71, s[18:19]
	v_cndmask_b32_e64 v70, 0, v70, s[18:19]
	v_cndmask_b32_e64 v69, 0, v69, s[18:19]
	v_cndmask_b32_e64 v68, 0, v68, s[18:19]
	v_cmp_lt_i32_e64 s[18:19], -10, v32
	v_cmp_gt_i32_e64 s[20:21], s92, v33
	s_and_b64 s[18:19], s[18:19], s[20:21]
	v_add_u32_e32 v33, 10, v32
	s_waitcnt vmcnt(1)
	v_cndmask_b32_e64 v107, 0, v107, s[18:19]
	v_cndmask_b32_e64 v106, 0, v106, s[18:19]
	v_cndmask_b32_e64 v105, 0, v105, s[18:19]
	v_cndmask_b32_e64 v104, 0, v104, s[18:19]
	v_cmp_lt_i32_e64 s[18:19], -11, v32
	v_cmp_gt_i32_e64 s[20:21], s92, v33
	ds_read_b128 v[60:63], v150
	ds_read_b128 v[52:55], v150 offset:16
	ds_read_b128 v[44:47], v150 offset:528
	ds_read_b128 v[56:59], v150 offset:512
	ds_read_b128 v[40:43], v150 offset:1040
	ds_read_b128 v[48:51], v150 offset:1024
	ds_read_b128 v[120:123], v150 offset:2064
	ds_read_b128 v[124:127], v150 offset:2048
	ds_read_b128 v[32:35], v150 offset:1552
	ds_read_b128 v[36:39], v150 offset:1536
	v_lshlrev_b32_e32 v66, 16, v68
	v_and_b32_e32 v67, 0xffff0000, v68
	v_lshlrev_b32_e32 v154, 16, v69
	v_and_b32_e32 v155, 0xffff0000, v69
	v_lshlrev_b32_e32 v168, 16, v70
	v_and_b32_e32 v169, 0xffff0000, v70
	s_waitcnt lgkmcnt(2)
	v_pk_fma_f32 v[66:67], v[60:61], v[66:67], v[124:125]
	v_pk_fma_f32 v[154:155], v[62:63], v[154:155], v[126:127]
	v_pk_fma_f32 v[168:169], v[52:53], v[168:169], v[120:121]
	v_lshlrev_b32_e32 v170, 16, v71
	v_and_b32_e32 v171, 0xffff0000, v71
	v_lshlrev_b32_e32 v172, 16, v72
	v_and_b32_e32 v173, 0xffff0000, v72
	v_lshlrev_b32_e32 v174, 16, v73
	v_and_b32_e32 v175, 0xffff0000, v73
	v_lshlrev_b32_e32 v176, 16, v74
	v_and_b32_e32 v177, 0xffff0000, v74
	v_pk_fma_f32 v[170:171], v[54:55], v[170:171], v[122:123]
	v_pk_fma_f32 v[66:67], v[56:57], v[172:173], v[66:67]
	v_pk_fma_f32 v[154:155], v[58:59], v[174:175], v[154:155]
	v_pk_fma_f32 v[168:169], v[44:45], v[176:177], v[168:169]
	v_lshlrev_b32_e32 v178, 16, v75
	v_and_b32_e32 v179, 0xffff0000, v75
	v_lshlrev_b32_e32 v180, 16, v76
	v_and_b32_e32 v181, 0xffff0000, v76
	v_lshlrev_b32_e32 v182, 16, v77
	v_and_b32_e32 v183, 0xffff0000, v77
	v_lshlrev_b32_e32 v184, 16, v78
	v_and_b32_e32 v185, 0xffff0000, v78
	v_pk_fma_f32 v[170:171], v[46:47], v[178:179], v[170:171]
	v_pk_fma_f32 v[66:67], v[48:49], v[180:181], v[66:67]
	v_pk_fma_f32 v[154:155], v[50:51], v[182:183], v[154:155]
	v_pk_fma_f32 v[168:169], v[40:41], v[184:185], v[168:169]
	v_lshlrev_b32_e32 v186, 16, v79
	v_and_b32_e32 v187, 0xffff0000, v79
	v_lshlrev_b32_e32 v188, 16, v80
	v_and_b32_e32 v189, 0xffff0000, v80
	v_lshlrev_b32_e32 v190, 16, v81
	v_and_b32_e32 v191, 0xffff0000, v81
	v_lshlrev_b32_e32 v192, 16, v82
	v_and_b32_e32 v193, 0xffff0000, v82
	v_pk_fma_f32 v[170:171], v[42:43], v[186:187], v[170:171]
	s_waitcnt lgkmcnt(0)
; #define LAS __attribute__((address_space(3)))
; __device__ __forceinline__ unsigned cvt_pk_bf16(float lo, float hi) { unsigned r; asm volatile("v_cvt_pk_bf16_f32 %0, %1, %2" : "=v"(r) : "v"(lo), "v"(hi)); return r; }
; __device__ __forceinline__ float bf_lo(unsigned u) { return __uint_as_float(u << 16); }
; __device__ __forceinline__ float bf_hi(unsigned u) { return __uint_as_float(u & 0xffff0000u); }
; template <int dir>
; __device__ __forceinline__ void lru_pass(LAS unsigned char* lds, const Params& P, int b, int h, int q, bool dry) {
;     ...
; #pragma unroll
;             for (int j = 0; j < 8; ++j) {
;                 f32x2 o0 = cb2[0], o1 = cb2[1], o2 = cb2[2], o3 = cb2[3];
; #pragma unroll
;                 for (int k = 0; k < 4; ++k) { const u32x4 rr = rows[j + k];
;                     o0 = cw2[k][0] * (f32x2){bf_lo(rr.x), bf_hi(rr.x)} + o0; o1 = cw2[k][1] * (f32x2){bf_lo(rr.y), bf_hi(rr.y)} + o1;
;                     o2 = cw2[k][2] * (f32x2){bf_lo(rr.z), bf_hi(rr.z)} + o2; o3 = cw2[k][3] * (f32x2){bf_lo(rr.w), bf_hi(rr.w)} + o3; }
;                 u32x4 w; w.x = cvt_pk_bf16(o0[0], o0[1]); w.y = cvt_pk_bf16(o1[0], o1[1]); w.z = cvt_pk_bf16(o2[0], o2[1]); w.w = cvt_pk_bf16(o3[0], o3[1]);
;                 *(LAS u32x4*)(XC + (tr * 8 + j) * XC_PITCH + cgp * 16) = w;
;             }
	v_pk_fma_f32 v[66:67], v[36:37], v[188:189], v[66:67]
	v_pk_fma_f32 v[154:155], v[38:39], v[190:191], v[154:155]
	v_pk_fma_f32 v[194:195], v[32:33], v[192:193], v[168:169]
	v_lshlrev_b32_e32 v196, 16, v83
	v_and_b32_e32 v197, 0xffff0000, v83
	v_cvt_pk_bf16_f32 v168, v66, v67
	v_cvt_pk_bf16_f32 v169, v154, v155
	v_pk_fma_f32 v[198:199], v[34:35], v[196:197], v[170:171]
	v_cvt_pk_bf16_f32 v170, v194, v195
	v_pk_fma_f32 v[66:67], v[60:61], v[172:173], v[124:125]
	v_cvt_pk_bf16_f32 v171, v198, v199
	ds_write_b128 v151, v[168:171]
	v_pk_fma_f32 v[154:155], v[62:63], v[174:175], v[126:127]
	v_pk_fma_f32 v[168:169], v[52:53], v[176:177], v[120:121]
	v_pk_fma_f32 v[170:171], v[54:55], v[178:179], v[122:123]
	v_pk_fma_f32 v[66:67], v[56:57], v[180:181], v[66:67]
	v_pk_fma_f32 v[154:155], v[58:59], v[182:183], v[154:155]
	v_pk_fma_f32 v[168:169], v[44:45], v[184:185], v[168:169]
	v_pk_fma_f32 v[170:171], v[46:47], v[186:187], v[170:171]
	v_pk_fma_f32 v[66:67], v[48:49], v[188:189], v[66:67]
	v_pk_fma_f32 v[154:155], v[50:51], v[190:191], v[154:155]
	v_pk_fma_f32 v[168:169], v[40:41], v[192:193], v[168:169]
	v_lshlrev_b32_e32 v172, 16, v84
	v_and_b32_e32 v173, 0xffff0000, v84
	v_lshlrev_b32_e32 v174, 16, v85
	v_and_b32_e32 v175, 0xffff0000, v85
	v_lshlrev_b32_e32 v176, 16, v86
	v_and_b32_e32 v177, 0xffff0000, v86
	v_pk_fma_f32 v[170:171], v[42:43], v[196:197], v[170:171]
	v_pk_fma_f32 v[66:67], v[36:37], v[172:173], v[66:67]
	v_pk_fma_f32 v[154:155], v[38:39], v[174:175], v[154:155]
	v_pk_fma_f32 v[178:179], v[32:33], v[176:177], v[168:169]
	v_lshlrev_b32_e32 v194, 16, v87
	v_and_b32_e32 v195, 0xffff0000, v87
	v_cvt_pk_bf16_f32 v168, v66, v67
	v_cvt_pk_bf16_f32 v169, v154, v155
	v_pk_fma_f32 v[198:199], v[34:35], v[194:195], v[170:171]
	v_cvt_pk_bf16_f32 v170, v178, v179
	v_pk_fma_f32 v[66:67], v[60:61], v[180:181], v[124:125]
	v_cvt_pk_bf16_f32 v171, v198, v199
	ds_write_b128 v151, v[168:171] offset:272
	v_pk_fma_f32 v[154:155], v[62:63], v[182:183], v[126:127]
	v_pk_fma_f32 v[168:169], v[52:53], v[184:185], v[120:121]
	v_pk_fma_f32 v[170:171], v[54:55], v[186:187], v[122:123]
	v_pk_fma_f32 v[66:67], v[56:57], v[188:189], v[66:67]
	v_pk_fma_f32 v[154:155], v[58:59], v[190:191], v[154:155]
	v_pk_fma_f32 v[168:169], v[44:45], v[192:193], v[168:169]
	v_pk_fma_f32 v[170:171], v[46:47], v[196:197], v[170:171]
	v_pk_fma_f32 v[66:67], v[48:49], v[172:173], v[66:67]
	v_pk_fma_f32 v[154:155], v[50:51], v[174:175], v[154:155]
	v_pk_fma_f32 v[168:169], v[40:41], v[176:177], v[168:169]
	v_lshlrev_b32_e32 v178, 16, v88
	v_and_b32_e32 v179, 0xffff0000, v88
	v_lshlrev_b32_e32 v180, 16, v89
	v_and_b32_e32 v181, 0xffff0000, v89
	v_lshlrev_b32_e32 v182, 16, v90
	v_and_b32_e32 v183, 0xffff0000, v90
	v_pk_fma_f32 v[170:171], v[42:43], v[194:195], v[170:171]
	v_pk_fma_f32 v[66:67], v[36:37], v[178:179], v[66:67]
	v_pk_fma_f32 v[154:155], v[38:39], v[180:181], v[154:155]
	v_pk_fma_f32 v[184:185], v[32:33], v[182:183], v[168:169]
	v_lshlrev_b32_e32 v186, 16, v91
	v_and_b32_e32 v187, 0xffff0000, v91
	v_cvt_pk_bf16_f32 v168, v66, v67
	v_cvt_pk_bf16_f32 v169, v154, v155
	v_pk_fma_f32 v[198:199], v[34:35], v[186:187], v[170:171]
	v_cvt_pk_bf16_f32 v170, v184, v185
	v_pk_fma_f32 v[66:67], v[60:61], v[188:189], v[124:125]
	v_cvt_pk_bf16_f32 v171, v198, v199
	ds_write_b128 v151, v[168:171] offset:544
	v_pk_fma_f32 v[154:155], v[62:63], v[190:191], v[126:127]
	v_pk_fma_f32 v[168:169], v[52:53], v[192:193], v[120:121]
	v_pk_fma_f32 v[170:171], v[54:55], v[196:197], v[122:123]
	v_pk_fma_f32 v[66:67], v[56:57], v[172:173], v[66:67]
	v_pk_fma_f32 v[154:155], v[58:59], v[174:175], v[154:155]
	v_pk_fma_f32 v[168:169], v[44:45], v[176:177], v[168:169]
	v_pk_fma_f32 v[170:171], v[46:47], v[194:195], v[170:171]
	v_pk_fma_f32 v[66:67], v[48:49], v[178:179], v[66:67]
	v_pk_fma_f32 v[154:155], v[50:51], v[180:181], v[154:155]
	v_pk_fma_f32 v[168:169], v[40:41], v[182:183], v[168:169]
	v_lshlrev_b32_e32 v184, 16, v92
	v_and_b32_e32 v185, 0xffff0000, v92
	v_lshlrev_b32_e32 v188, 16, v93
	v_and_b32_e32 v189, 0xffff0000, v93
	v_lshlrev_b32_e32 v190, 16, v94
	v_and_b32_e32 v191, 0xffff0000, v94
	v_pk_fma_f32 v[170:171], v[42:43], v[186:187], v[170:171]
	v_pk_fma_f32 v[66:67], v[36:37], v[184:185], v[66:67]
	v_pk_fma_f32 v[154:155], v[38:39], v[188:189], v[154:155]
	v_pk_fma_f32 v[192:193], v[32:33], v[190:191], v[168:169]
	v_lshlrev_b32_e32 v196, 16, v95
	v_and_b32_e32 v197, 0xffff0000, v95
	v_cvt_pk_bf16_f32 v168, v66, v67
	v_cvt_pk_bf16_f32 v169, v154, v155
	v_pk_fma_f32 v[198:199], v[34:35], v[196:197], v[170:171]
	v_cvt_pk_bf16_f32 v170, v192, v193
	v_pk_fma_f32 v[66:67], v[60:61], v[172:173], v[124:125]
	v_cvt_pk_bf16_f32 v171, v198, v199
	ds_write_b128 v151, v[168:171] offset:816
	v_pk_fma_f32 v[154:155], v[62:63], v[174:175], v[126:127]
	v_pk_fma_f32 v[168:169], v[52:53], v[176:177], v[120:121]
	v_pk_fma_f32 v[170:171], v[54:55], v[194:195], v[122:123]
	v_pk_fma_f32 v[66:67], v[56:57], v[178:179], v[66:67]
	v_pk_fma_f32 v[154:155], v[58:59], v[180:181], v[154:155]
	v_pk_fma_f32 v[168:169], v[44:45], v[182:183], v[168:169]
	v_pk_fma_f32 v[170:171], v[46:47], v[186:187], v[170:171]
	v_pk_fma_f32 v[66:67], v[48:49], v[184:185], v[66:67]
	v_pk_fma_f32 v[154:155], v[50:51], v[188:189], v[154:155]
	v_pk_fma_f32 v[168:169], v[40:41], v[190:191], v[168:169]
	v_lshlrev_b32_e32 v172, 16, v96
	v_and_b32_e32 v173, 0xffff0000, v96
	v_lshlrev_b32_e32 v174, 16, v97
	v_and_b32_e32 v175, 0xffff0000, v97
	v_lshlrev_b32_e32 v176, 16, v98
	v_and_b32_e32 v177, 0xffff0000, v98
	v_pk_fma_f32 v[170:171], v[42:43], v[196:197], v[170:171]
	v_pk_fma_f32 v[66:67], v[36:37], v[172:173], v[66:67]
; #define LAS __attribute__((address_space(3)))
; __device__ __forceinline__ unsigned cvt_pk_bf16(float lo, float hi) { unsigned r; asm volatile("v_cvt_pk_bf16_f32 %0, %1, %2" : "=v"(r) : "v"(lo), "v"(hi)); return r; }
; __device__ __forceinline__ float bf_lo(unsigned u) { return __uint_as_float(u << 16); }
; __device__ __forceinline__ float bf_hi(unsigned u) { return __uint_as_float(u & 0xffff0000u); }
; template <int dir>
; __device__ __forceinline__ void lru_pass(LAS unsigned char* lds, const Params& P, int b, int h, int q, bool dry) {
;     ...
; #pragma unroll
;             for (int j = 0; j < 8; ++j) {
;                 f32x2 o0 = cb2[0], o1 = cb2[1], o2 = cb2[2], o3 = cb2[3];
; #pragma unroll
;                 for (int k = 0; k < 4; ++k) { const u32x4 rr = rows[j + k];
;                     o0 = cw2[k][0] * (f32x2){bf_lo(rr.x), bf_hi(rr.x)} + o0; o1 = cw2[k][1] * (f32x2){bf_lo(rr.y), bf_hi(rr.y)} + o1;
;                     o2 = cw2[k][2] * (f32x2){bf_lo(rr.z), bf_hi(rr.z)} + o2; o3 = cw2[k][3] * (f32x2){bf_lo(rr.w), bf_hi(rr.w)} + o3; }
;                 u32x4 w; w.x = cvt_pk_bf16(o0[0], o0[1]); w.y = cvt_pk_bf16(o1[0], o1[1]); w.z = cvt_pk_bf16(o2[0], o2[1]); w.w = cvt_pk_bf16(o3[0], o3[1]);
;                 *(LAS u32x4*)(XC + (tr * 8 + j) * XC_PITCH + cgp * 16) = w;
;             }
; #pragma unroll
;             for (int i = 0; i < NIN; ++i) { const int id = tid + i * NTHREADS;
;                 if (dir == 0) *(LAS u32x4*)(TIN + (id >> 2) * IO_NP + (id & 3) * 16) = inr[i];
;                 else *(LAS u32x4*)(TIN + (id >> 3) * IO_WP + (id & 7) * 16) = inr[i]; }
;             LruTile nxt = cur;
;             if (sc < 8) { nxt = lru_tile(Z, ZC, b, h, dir, sc + 1); lru_load_rows(rows, nxt, tr, cgp);
; #pragma unroll
;                 for (int i = 0; i < NIN; ++i) { const int id = tid + i * NTHREADS;
;                     if (dir == 0) inr[i] = *(const u32x4*)(Zg + (size_t)(nxt.t0 + (id >> 2)) * 128 + (id & 3) * 8);
;                     else inr[i] = *(const u32x4*)(Hg + (size_t)(nxt.t0 + (id >> 3)) * DM + (id & 7) * 4); } }
	v_pk_fma_f32 v[154:155], v[38:39], v[174:175], v[154:155]
	v_pk_fma_f32 v[192:193], v[32:33], v[176:177], v[168:169]
	v_lshlrev_b32_e32 v194, 16, v99
	v_and_b32_e32 v195, 0xffff0000, v99
	v_cvt_pk_bf16_f32 v168, v66, v67
	v_cvt_pk_bf16_f32 v169, v154, v155
	v_pk_fma_f32 v[198:199], v[34:35], v[194:195], v[170:171]
	v_cvt_pk_bf16_f32 v170, v192, v193
	v_pk_fma_f32 v[66:67], v[60:61], v[178:179], v[124:125]
	v_cvt_pk_bf16_f32 v171, v198, v199
	ds_write_b128 v151, v[168:171] offset:1088
	v_pk_fma_f32 v[154:155], v[62:63], v[180:181], v[126:127]
	v_pk_fma_f32 v[168:169], v[52:53], v[182:183], v[120:121]
	v_pk_fma_f32 v[170:171], v[54:55], v[186:187], v[122:123]
	v_pk_fma_f32 v[66:67], v[56:57], v[184:185], v[66:67]
	v_pk_fma_f32 v[154:155], v[58:59], v[188:189], v[154:155]
	v_pk_fma_f32 v[168:169], v[44:45], v[190:191], v[168:169]
	v_pk_fma_f32 v[170:171], v[46:47], v[196:197], v[170:171]
	v_pk_fma_f32 v[66:67], v[48:49], v[172:173], v[66:67]
	v_pk_fma_f32 v[154:155], v[50:51], v[174:175], v[154:155]
	v_pk_fma_f32 v[168:169], v[40:41], v[176:177], v[168:169]
	v_lshlrev_b32_e32 v178, 16, v100
	v_and_b32_e32 v179, 0xffff0000, v100
	v_lshlrev_b32_e32 v180, 16, v101
	v_and_b32_e32 v181, 0xffff0000, v101
	v_lshlrev_b32_e32 v182, 16, v102
	v_and_b32_e32 v183, 0xffff0000, v102
	v_pk_fma_f32 v[170:171], v[42:43], v[194:195], v[170:171]
	v_pk_fma_f32 v[66:67], v[36:37], v[178:179], v[66:67]
	v_pk_fma_f32 v[154:155], v[38:39], v[180:181], v[154:155]
	v_pk_fma_f32 v[186:187], v[32:33], v[182:183], v[168:169]
	v_lshlrev_b32_e32 v192, 16, v103
	v_and_b32_e32 v193, 0xffff0000, v103
	v_cvt_pk_bf16_f32 v168, v66, v67
	v_cvt_pk_bf16_f32 v169, v154, v155
	s_and_b64 s[18:19], s[18:19], s[20:21]
	v_pk_fma_f32 v[198:199], v[34:35], v[192:193], v[170:171]
	v_cvt_pk_bf16_f32 v170, v186, v187
	v_pk_fma_f32 v[66:67], v[60:61], v[184:185], v[124:125]
	v_cvt_pk_bf16_f32 v171, v198, v199
	ds_write_b128 v151, v[168:171] offset:1360
	v_pk_fma_f32 v[168:169], v[52:53], v[190:191], v[120:121]
	v_pk_fma_f32 v[60:61], v[60:61], v[172:173], v[124:125]
	v_pk_fma_f32 v[52:53], v[52:53], v[176:177], v[120:121]
	s_waitcnt vmcnt(0)
	v_cndmask_b32_e64 v108, 0, v108, s[18:19]
	v_pk_fma_f32 v[154:155], v[62:63], v[188:189], v[126:127]
	v_pk_fma_f32 v[66:67], v[56:57], v[172:173], v[66:67]
	v_pk_fma_f32 v[168:169], v[44:45], v[176:177], v[168:169]
	v_lshlrev_b32_e32 v184, 16, v104
	v_and_b32_e32 v185, 0xffff0000, v104
	v_lshlrev_b32_e32 v188, 16, v106
	v_and_b32_e32 v189, 0xffff0000, v106
	v_pk_fma_f32 v[62:63], v[62:63], v[174:175], v[126:127]
	v_pk_fma_f32 v[56:57], v[56:57], v[178:179], v[60:61]
	v_pk_fma_f32 v[44:45], v[44:45], v[182:183], v[52:53]
	v_cndmask_b32_e64 v109, 0, v109, s[18:19]
	v_pk_fma_f32 v[154:155], v[58:59], v[174:175], v[154:155]
	v_pk_fma_f32 v[66:67], v[48:49], v[178:179], v[66:67]
	v_pk_fma_f32 v[168:169], v[40:41], v[182:183], v[168:169]
	v_lshlrev_b32_e32 v186, 16, v105
	v_and_b32_e32 v187, 0xffff0000, v105
	v_pk_fma_f32 v[58:59], v[58:59], v[180:181], v[62:63]
	v_pk_fma_f32 v[48:49], v[48:49], v[184:185], v[56:57]
	v_pk_fma_f32 v[40:41], v[40:41], v[188:189], v[44:45]
	v_lshlrev_b32_e32 v44, 16, v108
	v_and_b32_e32 v45, 0xffff0000, v108
	v_cndmask_b32_e64 v110, 0, v110, s[18:19]
	v_pk_fma_f32 v[170:171], v[54:55], v[196:197], v[122:123]
	v_pk_fma_f32 v[154:155], v[50:51], v[180:181], v[154:155]
	v_pk_fma_f32 v[66:67], v[36:37], v[184:185], v[66:67]
	v_pk_fma_f32 v[54:55], v[54:55], v[194:195], v[122:123]
	v_pk_fma_f32 v[50:51], v[50:51], v[186:187], v[58:59]
	v_pk_fma_f32 v[36:37], v[36:37], v[44:45], v[48:49]
	v_lshlrev_b32_e32 v44, 16, v109
	v_and_b32_e32 v45, 0xffff0000, v109
	v_cndmask_b32_e64 v111, 0, v111, s[18:19]
	v_pk_fma_f32 v[170:171], v[46:47], v[194:195], v[170:171]
	v_pk_fma_f32 v[154:155], v[38:39], v[186:187], v[154:155]
	v_lshlrev_b32_e32 v196, 16, v107
	v_and_b32_e32 v197, 0xffff0000, v107
	v_pk_fma_f32 v[46:47], v[46:47], v[192:193], v[54:55]
	v_pk_fma_f32 v[38:39], v[38:39], v[44:45], v[50:51]
	v_lshlrev_b32_e32 v44, 16, v110
	v_and_b32_e32 v45, 0xffff0000, v110
	v_pk_fma_f32 v[170:171], v[42:43], v[192:193], v[170:171]
	v_pk_fma_f32 v[190:191], v[32:33], v[188:189], v[168:169]
	v_pk_fma_f32 v[42:43], v[42:43], v[196:197], v[46:47]
	v_pk_fma_f32 v[40:41], v[32:33], v[44:45], v[40:41]
	v_lshlrev_b32_e32 v32, 16, v111
	v_and_b32_e32 v33, 0xffff0000, v111
	v_pk_fma_f32 v[198:199], v[34:35], v[196:197], v[170:171]
	v_cvt_pk_bf16_f32 v168, v66, v67
	v_cvt_pk_bf16_f32 v169, v154, v155
	v_cvt_pk_bf16_f32 v170, v190, v191
	v_pk_fma_f32 v[42:43], v[34:35], v[32:33], v[42:43]
	v_cvt_pk_bf16_f32 v171, v198, v199
	ds_write_b128 v151, v[168:171] offset:1632
	v_cvt_pk_bf16_f32 v32, v36, v37
	v_cvt_pk_bf16_f32 v33, v38, v39
	v_cvt_pk_bf16_f32 v34, v40, v41
	v_cvt_pk_bf16_f32 v35, v42, v43
	s_cmp_eq_u32 s80, 0x80000
	ds_write_b128 v151, v[32:35] offset:1904
	ds_write_b128 v158, v[112:115]
	ds_write_b128 v159, v[116:119]
	s_cbranch_scc1 .LBB0_294
	v_lshl_add_u64 v[32:33], v[136:137], 0, s[80:81]
	global_load_dwordx4 v[68:71], v[32:33], off offset:-1280
	global_load_dwordx4 v[72:75], v[32:33], off offset:-1024
	global_load_dwordx4 v[76:79], v[32:33], off offset:-768
	global_load_dwordx4 v[80:83], v[32:33], off offset:-512
	global_load_dwordx4 v[84:87], v[32:33], off offset:-256
	global_load_dwordx4 v[88:91], v[32:33], off
	global_load_dwordx4 v[92:95], v[32:33], off offset:256
	global_load_dwordx4 v[96:99], v[32:33], off offset:512
	global_load_dwordx4 v[100:103], v[32:33], off offset:768
	global_load_dwordx4 v[104:107], v[32:33], off offset:1024
	v_lshl_add_u64 v[34:35], v[134:135], 0, s[80:81]
	global_load_dwordx4 v[108:111], v[32:33], off offset:1280
	global_load_dwordx4 v[112:115], v[34:35], off
	v_lshl_add_u64 v[32:33], v[132:133], 0, s[80:81]
	global_load_dwordx4 v[116:119], v[32:33], off
	s_movk_i32 s92, 0x800
	s_mov_b32 s20, s90
	s_branch .LBB0_295

; #define LAS __attribute__((address_space(3)))
; template <int dir>
; __device__ __forceinline__ void lru_pass(LAS unsigned char* lds, const Params& P, int b, int h, int q, bool dry) {
;     ...
;             f32x16 zr, zi;
; #pragma unroll
;             for (int v = 0; v < 16; ++v) { zr[v] = br; zi[v] = bi; }
;             const int sbase = 32 * wid + 16 * g;
;             { const int sl = 32 * wid + s_i; const int tlA = dir == 0 ? sl : 255 - sl;
;               const LAS unsigned char* ap = XC + tlA * XC_PITCH + 16 * g;
;               const LAS unsigned char* wrp = WB + nl * XC_PITCH + 16 * g; const LAS unsigned char* wip = wrp + 32 * XC_PITCH;
; #pragma unroll
;               for (int ks = 0; ks < 8; ++ks) { const bf16x8 A = *(const LAS bf16x8*)(ap + 32 * ks);
;                   const bf16x8 Br = *(const LAS bf16x8*)(wrp + 32 * ks), Bi = *(const LAS bf16x8*)(wip + 32 * ks);
;                   zr = __builtin_amdgcn_mfma_f32_32x32x16_bf16(A, Br, zr, 0, 0, 0); zi = __builtin_amdgcn_mfma_f32_32x32x16_bf16(A, Bi, zi, 0, 0, 0); } }
;             unsigned xcb[16], pk[16];
; #pragma unroll
;             for (int v = 0; v < 16; ++v) { const int s = sbase + v; const int tl = dir == 0 ? s : 255 - s; xcb[v] = *(const LAS bf16_t*)(XC + tl * XC_PITCH + chl * 2);
;                 if (dir == 0) pk[v] = *(const LAS bf16_t*)(TIN + tl * IO_NP + nl * 2); else pk[v] = *(const LAS unsigned*)(TIN + tl * IO_WP + nl * 4); }
;             float Pp = 1.f, E = 0.f;
; #pragma unroll
;             for (int v = 0; v < 16; ++v) {
;                 const float xcv = __uint_as_float(xcb[v] << 16);
;                 const float r = __builtin_amdgcn_rcpf(1.0f + __builtin_amdgcn_exp2f(zr[v]));
;                 const float ig = __builtin_amdgcn_rcpf(1.0f + __builtin_amdgcn_exp2f(zi[v]));
;                 const float a = __builtin_amdgcn_exp2f(cl * r);
;                 const float sq = __builtin_amdgcn_sqrtf(fmaf(-a, a, 1.0f));
;                 const float u = sq * ig * xcv;
;                 E = fmaf(a, E, u); Pp *= a; zr[v] = E; zi[v] = Pp; }
.Llruf_wres:
	ds_read_b128 v[120:123], v160
	ds_read_b128 v[124:127], v160 offset:32
	ds_read_b128 v[168:171], v160 offset:64
	ds_read_b128 v[172:175], v160 offset:96
	ds_read_b128 v[176:179], v160 offset:128
	ds_read_b128 v[180:183], v160 offset:160
	ds_read_b128 v[184:187], v160 offset:192
	ds_read_b128 v[188:191], v160 offset:224
	ds_read_b128 v[236:239], v161 offset:8704
	ds_read_b128 v[240:243], v161 offset:8736
	ds_read_b128 v[244:247], v161 offset:8768
	ds_read_b128 v[248:251], v161 offset:8800
	s_waitcnt lgkmcnt(11)
	v_mfma_f32_32x32x16_bf16 v[32:47], v[120:123], v[204:207], v[0:15]
	s_waitcnt lgkmcnt(10)
	v_mfma_f32_32x32x16_bf16 v[32:47], v[124:127], v[208:211], v[32:47]
	s_waitcnt lgkmcnt(9)
	v_mfma_f32_32x32x16_bf16 v[32:47], v[168:171], v[212:215], v[32:47]
	s_waitcnt lgkmcnt(8)
	v_mfma_f32_32x32x16_bf16 v[32:47], v[172:175], v[216:219], v[32:47]
	s_waitcnt lgkmcnt(7)
	v_mfma_f32_32x32x16_bf16 v[32:47], v[176:179], v[220:223], v[32:47]
	s_waitcnt lgkmcnt(6)
	v_mfma_f32_32x32x16_bf16 v[32:47], v[180:183], v[224:227], v[32:47]
	s_waitcnt lgkmcnt(5)
	v_mfma_f32_32x32x16_bf16 v[32:47], v[184:187], v[228:231], v[32:47]
	s_waitcnt lgkmcnt(4)
	v_mfma_f32_32x32x16_bf16 v[32:47], v[188:191], v[232:235], v[32:47]
	s_waitcnt lgkmcnt(3)
	v_mfma_f32_32x32x16_bf16 v[48:63], v[120:123], v[236:239], v[16:31]
	ds_read_b128 v[236:239], v161 offset:8832
	s_nop 8
	v_exp_f32_e32 v32, v32
	v_exp_f32_e32 v33, v33
	v_exp_f32_e32 v34, v34
	v_add_f32_e32 v32, 1.0, v32
	v_rcp_f32_e32 v32, v32
	s_waitcnt lgkmcnt(3)
	v_mfma_f32_32x32x16_bf16 v[48:63], v[124:127], v[240:243], v[48:63]
	ds_read_b128 v[240:243], v161 offset:8864
	v_add_f32_e32 v33, 1.0, v33
	v_mul_f32_e32 v32, v138, v32
	v_rcp_f32_e32 v33, v33
	s_nop 0
	v_mul_f32_e32 v33, v138, v33
	s_waitcnt lgkmcnt(3)
	v_mfma_f32_32x32x16_bf16 v[48:63], v[168:171], v[244:247], v[48:63]
	ds_read_b128 v[244:247], v161 offset:8896
	v_exp_f32_e32 v33, v33
	s_waitcnt lgkmcnt(3)
	v_mfma_f32_32x32x16_bf16 v[48:63], v[172:175], v[248:251], v[48:63]
	ds_read_b128 v[248:251], v161 offset:8928
	ds_read_u16 v152, v162
	ds_read_u16 v154, v162 offset:272
	ds_read_u16 v155, v162 offset:544
	ds_read_u16 v157, v162 offset:816
	ds_read_u16 v196, v162 offset:1088
	ds_read_u16 v197, v162 offset:1360
	s_waitcnt lgkmcnt(5)
	v_lshlrev_b32_e32 v152, 16, v152
	s_waitcnt lgkmcnt(4)
	v_lshlrev_b32_e32 v154, 16, v154
	v_mfma_f32_32x32x16_bf16 v[48:63], v[176:179], v[236:239], v[48:63]
	ds_read_u16 v177, v162 offset:1632
	ds_read_u16 v178, v162 offset:1904
	ds_read_u16 v127, v163
	ds_read_u16 v124, v163 offset:80
	ds_read_u16 v121, v163 offset:160
	ds_read_u16 v66, v163 offset:240
	ds_read_u16 v64, v163 offset:320
	ds_read_u16 v126, v163 offset:400
	ds_read_u16 v123, v163 offset:480
	ds_read_u16 v120, v163 offset:560
	v_mfma_f32_32x32x16_bf16 v[48:63], v[180:183], v[240:243], v[48:63]
	v_exp_f32_e32 v171, v32
	ds_read_u16 v179, v162 offset:2176
	ds_read_u16 v180, v162 offset:2448
	ds_read_u16 v181, v162 offset:2720
	v_mfma_f32_32x32x16_bf16 v[48:63], v[184:187], v[244:247], v[48:63]
	ds_read_u16 v182, v162 offset:2992
	ds_read_u16 v183, v162 offset:3264
	ds_read_u16 v184, v162 offset:3536
	ds_read_u16 v185, v162 offset:3808
	ds_read_u16 v187, v162 offset:4080
	v_mfma_f32_32x32x16_bf16 v[48:63], v[188:191], v[248:251], v[48:63]
	s_nop 11
	v_exp_f32_e32 v172, v48
	ds_read_u16 v170, v163 offset:640
	ds_read_u16 v169, v163 offset:720
	ds_read_u16 v168, v163 offset:800
	ds_read_u16 v166, v163 offset:880
	ds_read_u16 v125, v163 offset:960
	ds_read_u16 v122, v163 offset:1040
	ds_read_u16 v67, v163 offset:1120
	ds_read_u16 v48, v163 offset:1200
	v_add_f32_e32 v32, 1.0, v172
	v_fma_f32 v172, -v171, v171, 1.0
	v_rcp_f32_e32 v32, v32
	v_sqrt_f32_e32 v172, v172
	s_nop 0
	v_mul_f32_e32 v32, v172, v32
	v_exp_f32_e32 v172, v49
	v_mul_f32_e32 v49, v32, v152
	v_fma_f32 v152, -v33, v33, 1.0
	v_sqrt_f32_e32 v152, v152
	v_add_f32_e32 v32, 1.0, v172
	v_rcp_f32_e32 v32, v32
	v_fmac_f32_e32 v49, 0, v171
	v_mul_f32_e32 v32, v152, v32
	v_mul_f32_e32 v172, v32, v154
	v_add_f32_e32 v32, 1.0, v34
	v_rcp_f32_e32 v32, v32
	v_exp_f32_e32 v34, v50
	v_fmac_f32_e32 v172, v33, v49
	v_mul_f32_e32 v50, v171, v33
	v_mul_f32_e32 v32, v138, v32
	v_exp_f32_e32 v32, v32
	v_add_f32_e32 v33, 1.0, v34
	v_exp_f32_e32 v34, v35
	v_rcp_f32_e32 v33, v33
	v_fma_f32 v35, -v32, v32, 1.0
	v_sqrt_f32_e32 v35, v35
	v_add_f32_e32 v34, 1.0, v34
	v_rcp_f32_e32 v34, v34
	s_waitcnt lgkmcnt(14)
; template <int dir>
; __device__ __forceinline__ void lru_pass(LAS unsigned char* lds, const Params& P, int b, int h, int q, bool dry) {
;     ...
;             float Pp = 1.f, E = 0.f;
; #pragma unroll
;             for (int v = 0; v < 16; ++v) {
;                 const float xcv = __uint_as_float(xcb[v] << 16);
;                 const float r = __builtin_amdgcn_rcpf(1.0f + __builtin_amdgcn_exp2f(zr[v]));
;                 const float ig = __builtin_amdgcn_rcpf(1.0f + __builtin_amdgcn_exp2f(zi[v]));
;                 const float a = __builtin_amdgcn_exp2f(cl * r);
;                 const float sq = __builtin_amdgcn_sqrtf(fmaf(-a, a, 1.0f));
;                 const float u = sq * ig * xcv;
;                 E = fmaf(a, E, u); Pp *= a; zr[v] = E; zi[v] = Pp; }
;             const float Po = __shfl_xor(Pp, 32), Eo = __shfl_xor(E, 32);
;             const float P0 = g ? Po : Pp, E0 = g ? Eo : E, P1 = g ? Pp : Po, E1 = g ? E : Eo;
;             if (g == 0) { AGG[(wid * 2 + 0) * 32 + nl] = P0 * P1; AGG[(wid * 2 + 1) * 32 + nl] = fmaf(P1, E0, E1); }
	v_lshlrev_b32_e32 v152, 16, v155
	v_mul_f32_e32 v33, v35, v33
	v_mul_f32_e32 v173, v33, v152
	v_mul_f32_e32 v34, v138, v34
	v_exp_f32_e32 v33, v51
	v_exp_f32_e32 v34, v34
	v_fmac_f32_e32 v173, v32, v172
	v_mul_f32_e32 v51, v32, v50
	v_exp_f32_e32 v32, v36
	v_add_f32_e32 v33, 1.0, v33
	v_fma_f32 v35, -v34, v34, 1.0
	v_rcp_f32_e32 v33, v33
	v_sqrt_f32_e32 v35, v35
	v_add_f32_e32 v32, 1.0, v32
	v_rcp_f32_e32 v32, v32
	v_lshlrev_b32_e32 v36, 16, v157
	v_mul_f32_e32 v33, v35, v33
	v_mul_f32_e32 v174, v33, v36
	v_mul_f32_e32 v32, v138, v32
	v_fmac_f32_e32 v174, v34, v173
	v_exp_f32_e32 v33, v52
	v_mul_f32_e32 v52, v34, v51
	v_exp_f32_e32 v32, v32
	v_exp_f32_e32 v34, v37
	v_add_f32_e32 v33, 1.0, v33
	v_rcp_f32_e32 v33, v33
	v_fma_f32 v35, -v32, v32, 1.0
	v_add_f32_e32 v34, 1.0, v34
	v_sqrt_f32_e32 v35, v35
	v_rcp_f32_e32 v34, v34
	v_lshlrev_b32_e32 v36, 16, v196
	v_mul_f32_e32 v33, v35, v33
	v_mul_f32_e32 v34, v138, v34
	v_mul_f32_e32 v175, v33, v36
	v_exp_f32_e32 v33, v53
	v_exp_f32_e32 v34, v34
	v_fmac_f32_e32 v175, v32, v174
	v_mul_f32_e32 v53, v32, v52
	v_exp_f32_e32 v32, v38
	v_add_f32_e32 v33, 1.0, v33
	v_fma_f32 v35, -v34, v34, 1.0
	v_rcp_f32_e32 v33, v33
	v_sqrt_f32_e32 v35, v35
	v_add_f32_e32 v32, 1.0, v32
	v_rcp_f32_e32 v32, v32
	v_lshlrev_b32_e32 v36, 16, v197
	v_mul_f32_e32 v33, v35, v33
	v_mul_f32_e32 v176, v33, v36
	v_mul_f32_e32 v32, v138, v32
	v_fmac_f32_e32 v176, v34, v175
	v_exp_f32_e32 v33, v54
	v_mul_f32_e32 v54, v34, v53
	v_exp_f32_e32 v32, v32
	v_exp_f32_e32 v34, v39
	v_add_f32_e32 v33, 1.0, v33
	v_rcp_f32_e32 v33, v33
	v_fma_f32 v35, -v32, v32, 1.0
	v_add_f32_e32 v34, 1.0, v34
	v_sqrt_f32_e32 v35, v35
	v_rcp_f32_e32 v34, v34
	v_lshlrev_b32_e32 v36, 16, v177
	v_mul_f32_e32 v33, v35, v33
	v_mul_f32_e32 v34, v138, v34
	v_mul_f32_e32 v177, v33, v36
	v_exp_f32_e32 v33, v55
	v_exp_f32_e32 v34, v34
	v_fmac_f32_e32 v177, v32, v176
	v_mul_f32_e32 v55, v32, v54
	v_exp_f32_e32 v32, v40
	v_add_f32_e32 v33, 1.0, v33
	v_fma_f32 v35, -v34, v34, 1.0
	v_rcp_f32_e32 v33, v33
	v_sqrt_f32_e32 v35, v35
	v_add_f32_e32 v32, 1.0, v32
	v_rcp_f32_e32 v32, v32
	v_lshlrev_b32_e32 v36, 16, v178
	v_mul_f32_e32 v33, v35, v33
	v_mul_f32_e32 v178, v33, v36
	v_mul_f32_e32 v32, v138, v32
	v_fmac_f32_e32 v178, v34, v177
	v_exp_f32_e32 v33, v56
	v_mul_f32_e32 v56, v34, v55
	v_exp_f32_e32 v32, v32
	v_exp_f32_e32 v34, v41
	v_add_f32_e32 v33, 1.0, v33
	v_rcp_f32_e32 v33, v33
	v_fma_f32 v35, -v32, v32, 1.0
	v_add_f32_e32 v34, 1.0, v34
	v_sqrt_f32_e32 v35, v35
	v_rcp_f32_e32 v34, v34
	v_lshlrev_b32_e32 v36, 16, v179
	v_mul_f32_e32 v33, v35, v33
	v_mul_f32_e32 v34, v138, v34
	v_mul_f32_e32 v179, v33, v36
	v_exp_f32_e32 v33, v57
	v_exp_f32_e32 v34, v34
	v_fmac_f32_e32 v179, v32, v178
	v_mul_f32_e32 v57, v32, v56
	v_exp_f32_e32 v32, v42
	v_add_f32_e32 v33, 1.0, v33
	v_fma_f32 v35, -v34, v34, 1.0
	v_rcp_f32_e32 v33, v33
	v_sqrt_f32_e32 v35, v35
	v_add_f32_e32 v32, 1.0, v32
	v_rcp_f32_e32 v32, v32
	v_lshlrev_b32_e32 v36, 16, v180
	v_mul_f32_e32 v33, v35, v33
	v_mul_f32_e32 v180, v33, v36
	v_mul_f32_e32 v32, v138, v32
	v_fmac_f32_e32 v180, v34, v179
	v_exp_f32_e32 v33, v58
	v_mul_f32_e32 v58, v34, v57
	v_exp_f32_e32 v32, v32
	v_exp_f32_e32 v34, v43
	v_add_f32_e32 v33, 1.0, v33
	v_rcp_f32_e32 v33, v33
	v_fma_f32 v35, -v32, v32, 1.0
	v_add_f32_e32 v34, 1.0, v34
	v_sqrt_f32_e32 v35, v35
	v_rcp_f32_e32 v34, v34
	s_waitcnt lgkmcnt(13)
	v_lshlrev_b32_e32 v36, 16, v181
	v_mul_f32_e32 v33, v35, v33
	v_mul_f32_e32 v34, v138, v34
	v_mul_f32_e32 v181, v33, v36
	v_exp_f32_e32 v33, v59
	v_exp_f32_e32 v34, v34
	v_fmac_f32_e32 v181, v32, v180
	v_mul_f32_e32 v59, v32, v58
	v_exp_f32_e32 v32, v44
	v_add_f32_e32 v33, 1.0, v33
	v_fma_f32 v35, -v34, v34, 1.0
	v_rcp_f32_e32 v33, v33
	v_sqrt_f32_e32 v35, v35
	v_add_f32_e32 v32, 1.0, v32
	v_rcp_f32_e32 v32, v32
	s_waitcnt lgkmcnt(12)
	v_lshlrev_b32_e32 v36, 16, v182
	v_mul_f32_e32 v33, v35, v33
	v_mul_f32_e32 v182, v33, v36
	v_mul_f32_e32 v32, v138, v32
	v_fmac_f32_e32 v182, v34, v181
	v_exp_f32_e32 v33, v60
	v_mul_f32_e32 v60, v34, v59
	v_exp_f32_e32 v32, v32
	v_exp_f32_e32 v34, v45
	v_add_f32_e32 v33, 1.0, v33
	v_rcp_f32_e32 v33, v33
	v_fma_f32 v35, -v32, v32, 1.0
	v_add_f32_e32 v34, 1.0, v34
	v_sqrt_f32_e32 v35, v35
	v_rcp_f32_e32 v34, v34
	s_waitcnt lgkmcnt(11)
	v_lshlrev_b32_e32 v36, 16, v183
	v_mul_f32_e32 v33, v35, v33
	v_mul_f32_e32 v34, v138, v34
	v_mul_f32_e32 v183, v33, v36
	v_exp_f32_e32 v33, v61
	v_exp_f32_e32 v34, v34
	v_fmac_f32_e32 v183, v32, v182
	v_mul_f32_e32 v61, v32, v60
	v_exp_f32_e32 v32, v46
	v_add_f32_e32 v33, 1.0, v33
	v_fma_f32 v35, -v34, v34, 1.0
	v_rcp_f32_e32 v33, v33
	v_sqrt_f32_e32 v35, v35
	v_add_f32_e32 v32, 1.0, v32
	v_rcp_f32_e32 v32, v32
	s_waitcnt lgkmcnt(10)
	v_lshlrev_b32_e32 v36, 16, v184
	v_mul_f32_e32 v33, v35, v33
	v_mul_f32_e32 v184, v33, v36
	v_fmac_f32_e32 v184, v34, v183
	v_exp_f32_e32 v33, v62
	v_mul_f32_e32 v62, v34, v61
	v_mul_f32_e32 v32, v138, v32
	v_exp_f32_e32 v34, v47
	v_exp_f32_e32 v32, v32
	v_add_f32_e32 v33, 1.0, v33
	v_rcp_f32_e32 v33, v33
	v_add_f32_e32 v34, 1.0, v34
	v_fma_f32 v35, -v32, v32, 1.0
	v_rcp_f32_e32 v34, v34
	v_sqrt_f32_e32 v35, v35
	s_waitcnt lgkmcnt(9)
	v_lshlrev_b32_e32 v36, 16, v185
	v_mul_f32_e32 v186, v32, v62
	v_mul_f32_e32 v34, v138, v34
	v_mul_f32_e32 v33, v35, v33
	v_exp_f32_e32 v35, v63
	v_exp_f32_e32 v34, v34
	v_mul_f32_e32 v63, v33, v36
	v_fmac_f32_e32 v63, v32, v184
	v_add_f32_e32 v33, 1.0, v35
	v_fma_f32 v35, -v34, v34, 1.0
	v_rcp_f32_e32 v33, v33
	v_sqrt_f32_e32 v35, v35
	s_waitcnt lgkmcnt(8)
	v_lshlrev_b32_e32 v32, 16, v187
	v_mul_f32_e32 v187, v34, v186
	v_mul_f32_e32 v33, v35, v33
	v_mul_f32_e32 v185, v33, v32
	v_and_b32_e32 v33, 64, v153
	v_xor_b32_e32 v32, 32, v153
	v_add_u32_e32 v33, 64, v33
	v_cmp_lt_i32_e64 s[18:19], v32, v33
	v_fmac_f32_e32 v185, v34, v63
	s_nop 0
	v_cndmask_b32_e64 v32, v153, v32, s[18:19]
	v_lshlrev_b32_e32 v157, 2, v32
	ds_bpermute_b32 v188, v157, v187
	ds_bpermute_b32 v189, v157, v185
	s_and_saveexec_b64 s[18:19], vcc
	s_cbranch_execz .LBB0_299
	s_waitcnt lgkmcnt(0)
	v_fma_f32 v32, v188, v185, v189
	v_mul_f32_e32 v33, v187, v188
	v_add_u32_e32 v35, s98, v147
	ds_write2_b32 v35, v33, v32 offset1:32
; #define LAS __attribute__((address_space(3)))
; __device__ __forceinline__ unsigned cvt_pk_bf16(float lo, float hi) { unsigned r; asm volatile("v_cvt_pk_bf16_f32 %0, %1, %2" : "=v"(r) : "v"(lo), "v"(hi)); return r; }
; __device__ __forceinline__ float bf_lo(unsigned u) { return __uint_as_float(u << 16); }
; __device__ __forceinline__ float bf_hi(unsigned u) { return __uint_as_float(u & 0xffff0000u); }
; __device__ __forceinline__ bf16_t f2bf(float f) { return (bf16_t)(cvt_pk_bf16(f, 0.f) & 0xffffu); }
; #define LDS_BARRIER() do { asm volatile("s_waitcnt lgkmcnt(0)" ::: "memory"); __builtin_amdgcn_s_barrier(); asm volatile("" ::: "memory"); } while (0)
; template <int dir>
; __device__ __forceinline__ void lru_pass(LAS unsigned char* lds, const Params& P, int b, int h, int q, bool dry) {
;     ...
;             LDS_BARRIER();
;             float cin = carry, cend = carry;
; #pragma unroll
;             for (int w = 0; w < 8; ++w) { const float pw = AGG[(w * 2 + 0) * 32 + nl], ew = AGG[(w * 2 + 1) * 32 + nl]; if (w == wid) cin = cend; cend = fmaf(pw, cend, ew); }
;             carry = cend;
;             if (g) cin = fmaf(P0, cin, E0);
;             if (!isctx) {
; #pragma unroll
;                 for (int v = 0; v < 16; ++v) { const float hv = fmaf(zi[v], cin, zr[v]);
;                     const int s = sbase + v; const int tl = dir == 0 ? s : 255 - s;
;                     if (dir == 0) *(LAS unsigned*)(TOUT + tl * IO_WP + nl * 4) = (cvt_pk_bf16(hv, 0.f) & 0xffffu) | (pk[v] << 16);
;                     else *(LAS bf16_t*)(TOUT + tl * IO_NP + nl * 2) = f2bf((bf_lo(pk[v]) + hv) * bf_hi(pk[v])); }
;             }
;             t0_prev = t0;
;             cur = nxt;
;         }
.LBB0_299:
	s_or_b64 exec, exec, s[18:19]
	s_waitcnt lgkmcnt(0)
	s_barrier
	v_add_u32_e32 v34, s99, v140
	ds_read2_b32 v[36:37], v34 offset1:32
	ds_read2_b32 v[38:39], v34 offset0:64 offset1:96
	ds_read2_b32 v[40:41], v34 offset0:128 offset1:160
	ds_read2_b32 v[42:43], v34 offset0:192 offset1:224
	v_add_u32_e32 v32, s100, v140
	ds_read2_b32 v[44:45], v32 offset1:32
	s_waitcnt lgkmcnt(4)
	v_fmac_f32_e32 v37, v36, v165
	ds_read2_b32 v[46:47], v32 offset0:64 offset1:96
	s_waitcnt lgkmcnt(4)
	v_fmac_f32_e32 v39, v38, v37
	ds_read2_b32 v[34:35], v32 offset0:128 offset1:160
	s_waitcnt lgkmcnt(4)
	v_fmac_f32_e32 v41, v40, v39
	ds_read2_b32 v[32:33], v32 offset0:192 offset1:224
	s_waitcnt lgkmcnt(4)
	v_fmac_f32_e32 v43, v42, v41
	s_waitcnt lgkmcnt(3)
	v_fmac_f32_e32 v45, v44, v43
	s_waitcnt lgkmcnt(2)
	v_fmac_f32_e32 v47, v46, v45
	s_cmp_eq_u32 s80, 0
	s_waitcnt lgkmcnt(1)
	v_fmac_f32_e32 v35, v34, v47
	s_cbranch_scc1 .LBB0_301
	v_cndmask_b32_e64 v37, v165, v37, s[14:15]
	v_cndmask_b32_e64 v37, v37, v39, s[12:13]
	v_cndmask_b32_e64 v37, v37, v41, s[10:11]
	v_cndmask_b32_e64 v37, v37, v43, s[8:9]
	v_cndmask_b32_e64 v37, v37, v45, s[4:5]
	v_cndmask_b32_e64 v37, v37, v47, s[16:17]
	v_cndmask_b32_e32 v34, v188, v187, vcc
	v_cndmask_b32_e32 v36, v189, v185, vcc
	v_cndmask_b32_e64 v37, v37, v35, s[0:1]
	v_fmac_f32_e32 v36, v34, v37
	v_cndmask_b32_e32 v34, v36, v37, vcc
	v_fmac_f32_e32 v49, v171, v34
	v_cvt_pk_bf16_f32 v36, v49, v65
	v_lshlrev_b32_e32 v37, 16, v127
	v_and_or_b32 v36, v36, s31, v37
	ds_write_b32 v164, v36
	v_fmac_f32_e32 v172, v50, v34
	v_cvt_pk_bf16_f32 v36, v172, v65
	v_lshlrev_b32_e32 v37, 16, v124
	v_and_or_b32 v36, v36, s31, v37
	ds_write_b32 v164, v36 offset:144
	v_fmac_f32_e32 v173, v51, v34
	v_cvt_pk_bf16_f32 v36, v173, v65
	v_lshlrev_b32_e32 v37, 16, v121
	v_and_or_b32 v36, v36, s31, v37
	ds_write_b32 v164, v36 offset:288
	v_fmac_f32_e32 v174, v52, v34
	v_cvt_pk_bf16_f32 v36, v174, v65
	v_lshlrev_b32_e32 v37, 16, v66
	v_and_or_b32 v36, v36, s31, v37
	ds_write_b32 v164, v36 offset:432
	v_fmac_f32_e32 v175, v53, v34
	v_cvt_pk_bf16_f32 v36, v175, v65
	v_lshlrev_b32_e32 v37, 16, v64
	v_and_or_b32 v36, v36, s31, v37
	ds_write_b32 v164, v36 offset:576
	v_fmac_f32_e32 v176, v54, v34
	v_cvt_pk_bf16_f32 v36, v176, v65
	v_lshlrev_b32_e32 v37, 16, v126
	v_and_or_b32 v36, v36, s31, v37
	ds_write_b32 v164, v36 offset:720
	v_fmac_f32_e32 v177, v55, v34
	v_cvt_pk_bf16_f32 v36, v177, v65
	v_lshlrev_b32_e32 v37, 16, v123
	v_and_or_b32 v36, v36, s31, v37
	ds_write_b32 v164, v36 offset:864
	v_fmac_f32_e32 v178, v56, v34
	v_cvt_pk_bf16_f32 v36, v178, v65
	v_lshlrev_b32_e32 v37, 16, v120
	v_and_or_b32 v36, v36, s31, v37
	ds_write_b32 v164, v36 offset:1008
	v_fmac_f32_e32 v179, v57, v34
	v_cvt_pk_bf16_f32 v36, v179, v65
	v_lshlrev_b32_e32 v37, 16, v170
	v_and_or_b32 v36, v36, s31, v37
	ds_write_b32 v164, v36 offset:1152
	v_fmac_f32_e32 v180, v58, v34
	v_cvt_pk_bf16_f32 v36, v180, v65
	v_lshlrev_b32_e32 v37, 16, v169
	v_and_or_b32 v36, v36, s31, v37
	ds_write_b32 v164, v36 offset:1296
	v_fmac_f32_e32 v181, v59, v34
	v_cvt_pk_bf16_f32 v36, v181, v65
	v_lshlrev_b32_e32 v37, 16, v168
	v_and_or_b32 v36, v36, s31, v37
	ds_write_b32 v164, v36 offset:1440
	v_fmac_f32_e32 v182, v60, v34
	v_cvt_pk_bf16_f32 v36, v182, v65
	v_lshlrev_b32_e32 v37, 16, v166
	v_and_or_b32 v36, v36, s31, v37
	ds_write_b32 v164, v36 offset:1584
	v_fmac_f32_e32 v183, v61, v34
	v_cvt_pk_bf16_f32 v36, v183, v65
	v_lshlrev_b32_e32 v37, 16, v125
	v_and_or_b32 v36, v36, s31, v37
	ds_write_b32 v164, v36 offset:1728
	v_fmac_f32_e32 v184, v62, v34
	v_cvt_pk_bf16_f32 v36, v184, v65
	v_lshlrev_b32_e32 v37, 16, v122
	v_and_or_b32 v36, v36, s31, v37
	ds_write_b32 v164, v36 offset:1872
	v_fmac_f32_e32 v63, v186, v34
	v_cvt_pk_bf16_f32 v36, v63, v65
	v_lshlrev_b32_e32 v37, 16, v67
	v_and_or_b32 v36, v36, s31, v37
	ds_write_b32 v164, v36 offset:2016
	v_fmac_f32_e32 v185, v187, v34
	v_cvt_pk_bf16_f32 v34, v185, v65
	v_lshlrev_b32_e32 v36, 16, v48
	v_and_or_b32 v34, v34, s31, v36
	ds_write_b32 v164, v34 offset:2160
.LBB0_301:
	s_xor_b32 s98, s98, 0x14000
	s_xor_b32 s99, s99, 0x14000
	s_xor_b32 s100, s100, 0x14000
	s_add_i32 s93, s93, 1
	s_addk_i32 s90, 0x100
	s_add_u32 s80, s80, 0x10000
	s_addc_u32 s81, s81, 0
	s_cmp_lg_u32 s80, 0x90000
	s_waitcnt lgkmcnt(0)
	v_fmac_f32_e32 v33, v32, v35
	s_cbranch_scc0 .LBB0_303
	v_mov_b32_e32 v165, v33
	s_mov_b32 s91, s97
	s_mov_b32 s97, s20
	s_branch .LBB0_292

; #define LAS __attribute__((address_space(3)))
; #define LDS_BARRIER() do { asm volatile("s_waitcnt lgkmcnt(0)" ::: "memory"); __builtin_amdgcn_s_barrier(); asm volatile("" ::: "memory"); } while (0)
; template <int dir>
; __device__ __forceinline__ void lru_pass(LAS unsigned char* lds, const Params& P, int b, int h, int q, bool dry) {
;     ...
;     {
; #pragma unroll
;         for (int i = 0; i < 2; ++i) { const int idx = tid + i * NTHREADS, gate = idx >> 9, n = (idx >> 4) & 31, kc = idx & 15;
;             *(LAS u32x4*)(WB + (gate * 32 + n) * XC_PITCH + kc * 16) = *(const u32x4*)(LruW + ((size_t)((dir * 2 + gate) * 8 + h) * 128 + q * 32 + n) * 128 + kc * 8); }
;         const float br = -LOG2E * P.lru_ba[(dir * 8 + h) * 128 + chl], bi = -LOG2E * P.lru_bx[(dir * 8 + h) * 128 + chl];
;         const float lam = P.lru_lambda[dir * 1024 + ch];
;         const float cl = -8.0f * LOG2E * log1pf(__expf(-lam));
;         float carry = 0.f;
;         LruTile cur = lru_tile(Z, ZC, b, h, dir, 0);
;         u32x4 rows[11];
;         constexpr int NIN = dir == 0 ? 2 : 4;
;         u32x4 inr[NIN];
;         lru_load_rows(rows, cur, tr, cgp);
;     ...
;         LDS_BARRIER();
;         if (dir == 0) {
; #pragma unroll
;             for (int i = 0; i < 4; ++i) { const int id = tid + i * NTHREADS; *(u32x4*)(Hg + (size_t)(t0_prev + (id >> 3)) * DM + (id & 7) * 4) = *(const LAS u32x4*)(TOUT + (id >> 3) * IO_WP + (id & 7) * 16); }
;         } else if (!dry) {
; #pragma unroll
;             for (int i = 0; i < 2; ++i) { const int id = tid + i * NTHREADS; *(u32x4*)(Z + ZSLAB(8 + h, (size_t)b * SEQ + t0_prev + (id >> 2)) + q * 32 + (id & 3) * 8) = *(const LAS u32x4*)(TOUT + (id >> 2) * IO_NP + (id & 3) * 16); }
;         }
.Lpp_f_noy:
	s_waitcnt lgkmcnt(0)
	s_barrier
	v_add_u32_e32 v0, v129, v149
	ds_read_b128 v[0:3], v0
	v_add_u32_e32 v4, s97, v148
	v_ashrrev_i32_e32 v5, 31, v4
	v_lshlrev_b64 v[4:5], 12, v[4:5]
	v_lshl_add_u64 v[8:9], v[130:131], 0, v[4:5]
	v_add_u32_e32 v4, v129, v146
	ds_read_b128 v[4:7], v4
	s_waitcnt lgkmcnt(1)
	global_store_dwordx4 v[8:9], v[0:3], off
	v_cmp_gt_i32_e32 vcc, 64, v128
	s_nop 0
	v_add_u32_e32 v0, s97, v145
	v_ashrrev_i32_e32 v1, 31, v0
	v_lshlrev_b64 v[0:1], 12, v[0:1]
	v_lshl_add_u64 v[0:1], v[130:131], 0, v[0:1]
	s_waitcnt lgkmcnt(0)
	global_store_dwordx4 v[0:1], v[4:7], off
	v_add_u32_e32 v0, v129, v144
	ds_read_b128 v[0:3], v0
	v_add_u32_e32 v4, s97, v143
	v_ashrrev_i32_e32 v5, 31, v4
	v_lshlrev_b64 v[4:5], 12, v[4:5]
	v_lshl_add_u64 v[8:9], v[130:131], 0, v[4:5]
	v_add_u32_e32 v4, v129, v142
	ds_read_b128 v[4:7], v4
	s_waitcnt lgkmcnt(1)
	global_store_dwordx4 v[8:9], v[0:3], off
	s_nop 1
	v_add_u32_e32 v0, s97, v141
	v_ashrrev_i32_e32 v1, 31, v0
	v_lshlrev_b64 v[0:1], 12, v[0:1]
	v_lshl_add_u64 v[0:1], v[130:131], 0, v[0:1]
	s_waitcnt lgkmcnt(0)
	global_store_dwordx4 v[0:1], v[4:7], off
	s_waitcnt lgkmcnt(0)
	v_mov_b32_e32 v32, v167
	s_barrier
	s_or_b32 s0, s26, 16
	v_and_b32_e32 v15, 31, v32
	v_or_b32_e32 v17, s28, v15
	v_add_u32_e32 v13, 0x200, v32
	v_or_b32_e32 v8, s27, v17
	v_ashrrev_i32_e32 v11, 9, v32
	v_ashrrev_i32_e32 v14, 9, v13
	v_lshlrev_b32_e32 v8, 2, v8
	v_mov_b32_e32 v9, v65
	v_lshl_add_u32 v2, v11, 3, s0
	v_lshl_add_u32 v6, v14, 3, s0
	v_lshl_add_u64 v[8:9], s[64:65], 0, v[8:9]
	s_movk_i32 s0, 0x1000
	v_add_co_u32_e32 v8, vcc, s0, v8
	v_and_b32_e32 v12, 15, v32
	s_nop 0
	v_addc_co_u32_e32 v9, vcc, 0, v9, vcc
	global_load_dword v16, v[8:9], off
	v_bfe_u32 v10, v32, 4, 5
	v_lshlrev_b32_e32 v64, 4, v12
	v_ashrrev_i32_e32 v3, 31, v2
	v_ashrrev_i32_e32 v7, 31, v6
	v_or_b32_e32 v4, s28, v10
	v_lshl_add_u64 v[0:1], s[38:39], 0, v[64:65]
	v_lshlrev_b64 v[2:3], 15, v[2:3]
	v_lshlrev_b64 v[6:7], 15, v[6:7]
	v_lshlrev_b32_e32 v4, 8, v4
	v_mov_b32_e32 v5, v65
	v_lshl_add_u64 v[2:3], v[0:1], 0, v[2:3]
	v_lshl_add_u64 v[0:1], v[0:1], 0, v[6:7]
	v_lshl_add_u64 v[2:3], v[2:3], 0, v[4:5]
	v_lshl_add_u64 v[4:5], v[0:1], 0, v[4:5]
	global_load_dwordx4 v[0:3], v[2:3], off
	s_nop 0
	global_load_dwordx4 v[4:7], v[4:5], off
	v_lshrrev_b32_e32 v8, 1, v32
	v_lshlrev_b32_e32 v9, 2, v32
	v_and_b32_e32 v20, 12, v8
	v_lshl_or_b32 v11, v11, 5, v10
	v_add_u32_e32 v8, s88, v64
	v_lshl_or_b32 v14, v14, 5, v10
	v_mad_u64_u32 v[10:11], s[6:7], v11, s89, v[8:9]
	s_or_b32 s8, s26, 8
	v_and_or_b32 v20, v9, 16, v20
	v_lshlrev_b32_e32 v21, 2, v17
	v_mad_u64_u32 v[8:9], s[6:7], v14, s89, v[8:9]
	v_lshl_or_b32 v9, s8, 9, v21
	global_load_dword v14, v9, s[58:59]
	s_nop 0
	global_load_dword v9, v9, s[62:63]
	s_mov_b32 s80, 0x3f2aaaab
	s_mov_b32 s81, 0x3f317218
	s_mov_b32 s91, 0x7f800000
	s_mov_b32 s92, 0x33800000
	v_ashrrev_i32_e32 v33, 4, v32
	v_lshlrev_b32_e32 v34, 3, v12
	v_readfirstlane_b32 s4, v32
	s_lshl_b64 s[0:1], s[78:79], 11
	s_lshl_b32 s5, s8, 14
	s_ashr_i32 s6, s4, 6
	s_add_u32 s26, s0, s5
	s_addc_u32 s27, s1, 0
	s_lshl_b32 s0, s28, 1
	v_readlane_b32 s1, v255, 10
	v_and_b32_e32 v19, 3, v32
	s_add_u32 s0, s1, s0
	v_bfe_u32 v18, v32, 5, 1
	v_add_u32_e32 v44, 0, v64
	v_lshlrev_b32_e32 v64, 4, v19
	s_addc_u32 s1, s3, 0
	v_lshl_add_u64 v[136:137], s[0:1], 0, v[64:65]
	s_lshl_b32 s0, s6, 5
	v_lshlrev_b32_e32 v46, 4, v18
	v_or_b32_e32 v37, s0, v46
	v_add_u32_e32 v158, s86, v64
	v_or_b32_e32 v64, 4, v37
	s_movk_i32 s93, 0x880
	v_ashrrev_i32_e32 v36, 3, v32
	v_ashrrev_i32_e32 v38, 3, v13
	v_ashrrev_i32_e32 v140, 2, v32
	v_sub_u32_e32 v39, 0xff, v37
	v_sub_u32_e32 v64, 0xff, v64
	v_lshl_add_u32 v160, v33, 3, -1
	v_mul_lo_u32 v52, v33, s93
	v_lshl_or_b32 v110, v33, 13, v34
	v_mov_b32_e32 v111, v65
	v_lshlrev_b64 v[110:111], 1, v[110:111]
	v_lshl_add_u64 v[108:109], s[48:49], 0, v[110:111]
	global_load_dwordx4 v[68:71], v[108:109], off offset:-2048
	global_load_dwordx4 v[72:75], v[108:109], off
	global_load_dwordx4 v[76:79], v[108:109], off offset:2048
	v_lshl_add_u64 v[108:109], s[50:51], 0, v[110:111]
	global_load_dwordx4 v[80:83], v[108:109], off
	v_lshl_add_u64 v[108:109], s[56:57], 0, v[110:111]
	global_load_dwordx4 v[84:87], v[108:109], off
	v_lshl_add_u64 v[108:109], s[60:61], 0, v[110:111]
	global_load_dwordx4 v[88:91], v[108:109], off
	v_lshl_add_u64 v[108:109], s[66:67], 0, v[110:111]
	global_load_dwordx4 v[92:95], v[108:109], off
	v_lshl_add_u64 v[108:109], s[70:71], 0, v[110:111]
	global_load_dwordx4 v[96:99], v[108:109], off
	v_lshl_add_u64 v[108:109], s[72:73], 0, v[110:111]
	global_load_dwordx4 v[100:103], v[108:109], off
	v_lshl_add_u64 v[108:109], s[74:75], 0, v[110:111]
	global_load_dwordx4 v[104:107], v[108:109], off
	v_lshl_add_u64 v[108:109], s[76:77], 0, v[110:111]
	global_load_dwordx4 v[108:111], v[108:109], off
	s_waitcnt vmcnt(14)
	ds_write_b128 v10, v[0:3]
	s_waitcnt vmcnt(13)
; template <int dir>
; __device__ __forceinline__ void lru_pass(LAS unsigned char* lds, const Params& P, int b, int h, int q, bool dry) {
;     ...
;         const float br = -LOG2E * P.lru_ba[(dir * 8 + h) * 128 + chl], bi = -LOG2E * P.lru_bx[(dir * 8 + h) * 128 + chl];
;         const float lam = P.lru_lambda[dir * 1024 + ch];
;         const float cl = -8.0f * LOG2E * log1pf(__expf(-lam));
;         float carry = 0.f;
;         LruTile cur = lru_tile(Z, ZC, b, h, dir, 0);
;         u32x4 rows[11];
;         constexpr int NIN = dir == 0 ? 2 : 4;
;         u32x4 inr[NIN];
;         lru_load_rows(rows, cur, tr, cgp);
; #pragma unroll
;         for (int i = 0; i < NIN; ++i) inr[i] = (u32x4){0u, 0u, 0u, 0u};
;         int t0_prev = 0;
	ds_write_b128 v8, v[4:7]
	v_mul_f32_e32 v11, 0xbfb8aa3b, v16
	v_exp_f32_e32 v11, v11
	v_mul_lo_u32 v57, v39, s89
	v_mul_lo_u32 v58, v39, s30
	v_mul_lo_u32 v114, v64, s89
	v_add_f32_e32 v2, 1.0, v11
	v_add_f32_e32 v3, -1.0, v2
	v_frexp_mant_f32_e32 v4, v2
	v_cvt_f64_f32_e32 v[0:1], v2
	v_sub_f32_e32 v5, v3, v2
	v_frexp_exp_i32_f64_e32 v0, v[0:1]
	v_cmp_gt_f32_e32 vcc, s80, v4
	v_sub_f32_e32 v3, v11, v3
	v_add_f32_e32 v1, 1.0, v5
	v_subbrev_co_u32_e32 v0, vcc, 0, v0, vcc
	v_add_f32_e32 v1, v3, v1
	v_sub_u32_e32 v3, 0, v0
	v_ldexp_f32 v2, v2, v3
	v_ldexp_f32 v1, v1, v3
	v_add_f32_e32 v3, -1.0, v2
	v_add_f32_e32 v4, 1.0, v2
	v_add_f32_e32 v5, 1.0, v3
	v_add_f32_e32 v6, -1.0, v4
	v_sub_f32_e32 v5, v2, v5
	v_sub_f32_e32 v2, v2, v6
	v_add_f32_e32 v5, v1, v5
	v_add_f32_e32 v1, v1, v2
	v_add_f32_e32 v7, v4, v1
	v_rcp_f32_e32 v8, v7
	v_add_f32_e32 v2, v3, v5
	v_sub_f32_e32 v4, v7, v4
	v_sub_f32_e32 v3, v2, v3
	v_sub_f32_e32 v1, v1, v4
	v_mul_f32_e32 v4, v2, v8
	v_sub_f32_e32 v3, v5, v3
	v_mul_f32_e32 v5, v7, v4
	v_fma_f32 v10, v4, v7, -v5
	v_fmac_f32_e32 v10, v4, v1
	v_add_f32_e32 v16, v5, v10
	v_sub_f32_e32 v21, v2, v16
	v_sub_f32_e32 v2, v2, v21
	v_sub_f32_e32 v5, v16, v5
	v_sub_f32_e32 v2, v2, v16
	v_sub_f32_e32 v5, v5, v10
	v_add_f32_e32 v2, v3, v2
	v_add_f32_e32 v2, v5, v2
	v_add_f32_e32 v3, v21, v2
	v_mul_f32_e32 v5, v8, v3
	v_sub_f32_e32 v10, v21, v3
	v_mul_f32_e32 v16, v7, v5
	v_add_f32_e32 v2, v2, v10
	v_add_f32_e32 v10, v4, v5
	v_fma_f32 v7, v5, v7, -v16
	v_sub_f32_e32 v4, v10, v4
	v_fmac_f32_e32 v7, v5, v1
	v_sub_f32_e32 v1, v5, v4
	v_add_f32_e32 v4, v16, v7
	v_sub_f32_e32 v5, v4, v16
	v_sub_f32_e32 v16, v3, v4
	v_sub_f32_e32 v3, v3, v16
	v_sub_f32_e32 v3, v3, v4
	v_cvt_f32_i32_e32 v0, v0
	v_sub_f32_e32 v5, v5, v7
	v_add_f32_e32 v2, v2, v3
	v_add_f32_e32 v2, v5, v2
	v_add_f32_e32 v2, v16, v2
	v_mul_f32_e32 v2, v8, v2
	v_mul_f32_e32 v6, 0x3f317218, v0
	v_add_f32_e32 v1, v1, v2
	v_add_f32_e32 v2, v10, v1
	v_fma_f32 v5, v0, s81, -v6
	v_fmac_f32_e32 v5, 0xb102e308, v0
	v_sub_f32_e32 v0, v2, v10
	v_mul_f32_e32 v3, v2, v2
	v_sub_f32_e32 v0, v1, v0
	v_add_f32_e32 v1, v6, v5
	v_fmamk_f32 v4, v3, 0x3e9b6dac, v200
	v_sub_f32_e32 v6, v1, v6
	v_fmaak_f32 v4, v3, v4, 0x3f2aaada
	v_sub_f32_e32 v5, v5, v6
	v_ldexp_f32 v6, v2, 1
	v_mul_f32_e32 v2, v2, v3
	v_mul_f32_e32 v2, v2, v4
	v_add_f32_e32 v3, v6, v2
	v_sub_f32_e32 v4, v3, v6
	v_ldexp_f32 v0, v0, 1
	v_sub_f32_e32 v2, v2, v4
	v_add_f32_e32 v0, v0, v2
	v_add_f32_e32 v2, v3, v0
	v_sub_f32_e32 v3, v2, v3
	v_sub_f32_e32 v0, v0, v3
	v_add_f32_e32 v3, v1, v2
	v_sub_f32_e32 v4, v3, v1
	v_sub_f32_e32 v6, v3, v4
	v_sub_f32_e32 v1, v1, v6
	v_sub_f32_e32 v2, v2, v4
	v_add_f32_e32 v1, v2, v1
	v_add_f32_e32 v2, v5, v0
	v_sub_f32_e32 v4, v2, v5
	v_add_f32_e32 v1, v2, v1
	v_sub_f32_e32 v6, v2, v4
	v_add_f32_e32 v2, v3, v1
	v_sub_f32_e32 v5, v5, v6
	v_sub_f32_e32 v0, v0, v4
	v_sub_f32_e32 v3, v2, v3
	v_add_f32_e32 v0, v0, v5
	v_sub_f32_e32 v1, v1, v3
	v_add_f32_e32 v0, v0, v1
	v_add_f32_e32 v0, v2, v0
	v_cmp_neq_f32_e32 vcc, s91, v11
	v_mov_b32_e32 v1, v65
	v_mul_lo_u32 v115, v64, s30
	v_cndmask_b32_e32 v0, v201, v0, vcc
	v_cmp_ngt_f32_e32 vcc, -1.0, v11
	v_mul_lo_u32 v206, v39, s87
	v_mul_lo_u32 v210, v64, s87
	v_cndmask_b32_e32 v0, v202, v0, vcc
	v_cmp_neq_f32_e32 vcc, -1.0, v11
	v_ashrrev_i32_e32 v39, 31, v38
	v_sub_u32_e32 v41, 0xfe, v37
	v_cndmask_b32_e32 v0, v203, v0, vcc
	v_cmp_lt_f32_e64 vcc, |v11|, s92
	v_mul_lo_u32 v59, v41, s89
	v_mul_lo_u32 v60, v41, s30
	v_cndmask_b32_e32 v6, v0, v11, vcc
	v_lshlrev_b32_e32 v2, 4, v32
	v_and_b32_e32 v2, 0x70, v2
	v_lshlrev_b32_e32 v1, 2, v15
	v_add_u32_e32 v45, s95, v2
	v_or3_b32 v2, v19, v20, s0
	s_and_b32 s0, s4, 0x3fffffc0
	v_add_u32_e32 v161, s94, v1
	s_cmp_eq_u32 s6, 7
	v_lshl_add_u32 v254, s0, 2, v161
	s_cselect_b64 s[0:1], -1, 0
	s_cmp_eq_u32 s6, 6
	s_cselect_b64 s[16:17], -1, 0
	s_cmp_eq_u32 s6, 5
	s_cselect_b64 s[4:5], -1, 0
	s_cmp_eq_u32 s6, 4
	s_cselect_b64 s[8:9], -1, 0
	s_cmp_eq_u32 s6, 3
	s_cselect_b64 s[10:11], -1, 0
	s_cmp_eq_u32 s6, 2
	s_cselect_b64 s[12:13], -1, 0
	s_cmp_eq_u32 s6, 1
	s_cselect_b64 s[14:15], -1, 0
	s_lshl_b32 s6, s25, 7
	s_and_b32 s6, s6, 0xe00
	s_lshl_b32 s7, s29, 7
	s_or_b32 s6, s7, s6
	s_add_u32 s6, s6, s44
	v_add_u32_e32 v50, s95, v1
	v_add_u32_e32 v1, 0x400, v32
	s_addc_u32 s7, 0, s45
	v_ashrrev_i32_e32 v40, 3, v1
	v_add_u32_e32 v1, 0x600, v32
	v_and_b32_e32 v32, 7, v32
	s_add_u32 s18, s84, s46
	v_lshlrev_b32_e32 v64, 4, v32
	v_lshl_or_b32 v32, v33, 10, v34
	v_mov_b32_e32 v33, v65
	s_addc_u32 s19, s85, s47
	v_lshl_add_u64 v[144:145], v[32:33], 1, s[18:19]
	v_lshlrev_b64 v[32:33], 12, v[38:39]
	v_lshl_add_u64 v[32:33], s[6:7], 0, v[32:33]
	v_mul_lo_u32 v207, v41, s87
	v_lshl_add_u64 v[32:33], v[32:33], 0, v[64:65]
	v_ashrrev_i32_e32 v41, 31, v40
	v_or_b32_e32 v43, 2, v37
	v_lshl_add_u64 v[252:253], s[42:43], 0, v[32:33]
	v_lshlrev_b64 v[32:33], 12, v[40:41]
	v_ashrrev_i32_e32 v42, 3, v1
	v_sub_u32_e32 v43, 0xff, v43
	v_or_b32_e32 v63, 3, v37
	v_or_b32_e32 v66, 5, v37
	v_or_b32_e32 v67, 6, v37
	v_or_b32_e32 v120, 7, v37
	v_or_b32_e32 v123, 8, v37
	v_or_b32_e32 v126, 9, v37
	v_or_b32_e32 v129, 10, v37
	v_or_b32_e32 v132, 11, v37
	v_or_b32_e32 v135, 12, v37
	v_or_b32_e32 v142, 13, v37
	v_or_b32_e32 v143, 14, v37
	v_or_b32_e32 v37, 15, v37
	v_lshl_add_u64 v[32:33], s[6:7], 0, v[32:33]
	v_mul_lo_u32 v61, v43, s89
	v_mul_lo_u32 v62, v43, s30
	v_sub_u32_e32 v37, 0xff, v37
	v_mul_lo_u32 v208, v43, s87
	v_lshl_add_u64 v[32:33], v[32:33], 0, v[64:65]
	v_ashrrev_i32_e32 v43, 31, v42
	v_sub_u32_e32 v2, 0xff, v2
	v_mul_lo_u32 v204, v37, s89
	v_mul_lo_u32 v205, v37, s30
	v_mul_lo_u32 v221, v37, s87
	v_ashrrev_i32_e32 v37, 31, v36
	v_lshl_add_u64 v[154:155], s[42:43], 0, v[32:33]
	v_lshlrev_b64 v[32:33], 12, v[42:43]
	v_mul_lo_u32 v2, v2, s89
	v_mul_lo_u32 v53, v36, s30
	v_sub_u32_e32 v63, 0xff, v63
	v_sub_u32_e32 v66, 0xff, v66
	v_sub_u32_e32 v67, 0xff, v67
	v_sub_u32_e32 v120, 0xff, v120
	v_sub_u32_e32 v123, 0xff, v123
	v_sub_u32_e32 v126, 0xff, v126
	v_lshlrev_b64 v[36:37], 12, v[36:37]
	v_lshl_add_u64 v[32:33], s[6:7], 0, v[32:33]
	v_lshlrev_b32_e32 v35, 5, v12
	v_add_u32_e32 v47, 0, v2
	v_mov_b32_e32 v2, s88
	v_lshl_add_u32 v49, v17, 1, 0
	v_lshl_add_u32 v51, v15, 1, s86
	v_mul_lo_u32 v112, v63, s89
	v_mul_lo_u32 v113, v63, s30
	v_mul_lo_u32 v116, v66, s89
	v_mul_lo_u32 v117, v66, s30
	v_mul_lo_u32 v118, v67, s89
	v_mul_lo_u32 v119, v67, s30
	v_mul_lo_u32 v121, v120, s89
	v_mul_lo_u32 v122, v120, s30
	v_mul_lo_u32 v124, v123, s89
	v_mul_lo_u32 v125, v123, s30
	v_mul_lo_u32 v127, v126, s89
	v_mul_lo_u32 v128, v126, s30
	v_sub_u32_e32 v129, 0xff, v129
	v_sub_u32_e32 v132, 0xff, v132
	v_sub_u32_e32 v135, 0xff, v135
	v_sub_u32_e32 v142, 0xff, v142
	v_sub_u32_e32 v143, 0xff, v143
	v_mul_lo_u32 v211, v66, s87
	v_mul_lo_u32 v212, v67, s87
	v_mul_lo_u32 v120, v120, s87
	v_mul_lo_u32 v123, v123, s87
	v_mul_lo_u32 v126, v126, s87
	v_lshl_add_u64 v[36:37], s[6:7], 0, v[36:37]
	v_lshl_add_u64 v[32:33], v[32:33], 0, v[64:65]
	v_mov_b32_e32 v66, v65
	v_mov_b32_e32 v67, v65
	s_waitcnt vmcnt(12)
; #define LAS __attribute__((address_space(3)))
; template <int dir>
; __device__ __forceinline__ void lru_pass(LAS unsigned char* lds, const Params& P, int b, int h, int q, bool dry) {
;     ...
;             f32x16 zr, zi;
; #pragma unroll
;             for (int v = 0; v < 16; ++v) { zr[v] = br; zi[v] = bi; }
;             const int sbase = 32 * wid + 16 * g;
;             { const int sl = 32 * wid + s_i; const int tlA = dir == 0 ? sl : 255 - sl;
;               const LAS unsigned char* ap = XC + tlA * XC_PITCH + 16 * g;
;               const LAS unsigned char* wrp = WB + nl * XC_PITCH + 16 * g; const LAS unsigned char* wip = wrp + 32 * XC_PITCH;
; #pragma unroll
;               for (int ks = 0; ks < 8; ++ks) { const bf16x8 A = *(const LAS bf16x8*)(ap + 32 * ks);
;                   const bf16x8 Br = *(const LAS bf16x8*)(wrp + 32 * ks), Bi = *(const LAS bf16x8*)(wip + 32 * ks);
;                   zr = __builtin_amdgcn_mfma_f32_32x32x16_bf16(A, Br, zr, 0, 0, 0); zi = __builtin_amdgcn_mfma_f32_32x32x16_bf16(A, Bi, zi, 0, 0, 0); } }
;             unsigned xcb[16], pk[16];
; #pragma unroll
;             for (int v = 0; v < 16; ++v) { const int s = sbase + v; const int tl = dir == 0 ? s : 255 - s; xcb[v] = *(const LAS bf16_t*)(XC + tl * XC_PITCH + chl * 2);
;                 if (dir == 0) pk[v] = *(const LAS bf16_t*)(TIN + tl * IO_NP + nl * 2); else pk[v] = *(const LAS unsigned*)(TIN + tl * IO_WP + nl * 4); }
	v_mul_f32_e32 v0, 0xbfb8aa3b, v14
	s_waitcnt vmcnt(11)
	v_mul_f32_e32 v16, 0xbfb8aa3b, v9
	v_mad_u32_u24 v48, v15, s89, v2
	v_mul_lo_u32 v54, v38, s30
	v_mul_lo_u32 v55, v40, s30
	v_mul_lo_u32 v56, v42, s30
	v_ashrrev_i32_e32 v138, 2, v13
	v_mul_lo_u32 v130, v129, s89
	v_mul_lo_u32 v131, v129, s30
	v_mul_lo_u32 v133, v132, s89
	v_mul_lo_u32 v134, v132, s30
	v_mul_lo_u32 v146, v135, s89
	v_mul_lo_u32 v147, v135, s30
	v_mul_lo_u32 v148, v142, s89
	v_mul_lo_u32 v149, v142, s30
	v_mul_lo_u32 v162, v143, s89
	v_mul_lo_u32 v163, v143, s30
	v_mul_lo_u32 v63, v63, s87
	v_mul_lo_u32 v129, v129, s87
	v_mul_lo_u32 v132, v132, s87
	v_mul_lo_u32 v135, v135, s87
	v_mul_lo_u32 v219, v142, s87
	v_mul_lo_u32 v220, v143, s87
	v_lshl_add_u64 v[36:37], v[36:37], 0, v[64:65]
	v_lshl_add_u64 v[150:151], s[42:43], 0, v[32:33]
	v_mov_b32_e32 v64, v65
	v_add_u32_e32 v32, 0, v35
	v_add_u32_e32 v180, v49, v112
	v_add_u32_e32 v181, v50, v113
	v_add_u32_e32 v182, v49, v114
	v_add_u32_e32 v183, v50, v115
	v_add_u32_e32 v184, v49, v116
	v_add_u32_e32 v185, v50, v117
	v_add_u32_e32 v186, v49, v118
	v_add_u32_e32 v187, v50, v119
	v_add_u32_e32 v188, v49, v121
	v_add_u32_e32 v189, v50, v122
	v_add_u32_e32 v190, v49, v124
	v_add_u32_e32 v191, v50, v125
	v_add_u32_e32 v192, v49, v127
	v_add_u32_e32 v213, v51, v120
	v_add_u32_e32 v214, v51, v123
	v_add_u32_e32 v215, v51, v126
	v_mov_b64_e32 v[114:115], v[66:67]
	v_mov_b64_e32 v[118:119], v[66:67]
	v_mov_b64_e32 v[122:123], v[66:67]
	v_mov_b64_e32 v[126:127], v[66:67]
	s_mov_b32 s78, 0
	v_mov_b32_e32 v156, 0xff800000
	v_mul_f32_e32 v159, 0xc138aa3b, v6
	v_cmp_eq_u32_e32 vcc, 0, v18
	v_mul_lo_u32 v164, v140, s87
	v_ashrrev_i32_e32 v141, 31, v140
	v_mul_lo_u32 v152, v138, s87
	v_ashrrev_i32_e32 v139, 31, v138
	v_mov_b32_e32 v1, v0
	v_mov_b32_e32 v2, v0
	v_mov_b32_e32 v3, v0
	v_mov_b32_e32 v4, v0
	v_mov_b32_e32 v5, v0
	v_mov_b32_e32 v6, v0
	v_mov_b32_e32 v7, v0
	v_mov_b32_e32 v8, v0
	v_mov_b32_e32 v9, v0
	v_mov_b32_e32 v10, v0
	v_mov_b32_e32 v11, v0
	v_mov_b32_e32 v12, v0
	v_mov_b32_e32 v13, v0
	v_mov_b32_e32 v14, v0
	v_mov_b32_e32 v15, v0
	v_mov_b32_e32 v17, v16
	v_mov_b32_e32 v18, v16
	v_mov_b32_e32 v19, v16
	v_mov_b32_e32 v20, v16
	v_mov_b32_e32 v21, v16
	v_mov_b32_e32 v22, v16
	v_mov_b32_e32 v23, v16
	v_mov_b32_e32 v24, v16
	v_mov_b32_e32 v25, v16
	v_mov_b32_e32 v26, v16
	v_mov_b32_e32 v27, v16
	v_mov_b32_e32 v28, v16
	v_mov_b32_e32 v29, v16
	v_mov_b32_e32 v30, v16
	v_mov_b32_e32 v31, v16
	v_lshl_add_u64 v[142:143], s[42:43], 0, v[36:37]
	s_movk_i32 s28, 0x100
	v_mov_b32_e32 v222, 0
	s_mov_b64 s[44:45], 0
	s_movk_i32 s25, 0x700
	v_add_u32_e32 v165, 0x15c00, v32
	v_add_u32_e32 v166, v44, v52
	v_add_u32_e32 v168, v45, v53
	v_add_u32_e32 v169, v45, v54
	v_add_u32_e32 v170, v45, v55
	v_add_u32_e32 v171, v45, v56
	v_add_u32_e32 v172, v47, v46
	v_add_u32_e32 v173, v48, v46
	v_add_u32_e32 v174, v49, v57
	v_add_u32_e32 v175, v50, v58
	v_add_u32_e32 v176, v49, v59
	v_add_u32_e32 v177, v50, v60
	v_add_u32_e32 v178, v49, v61
	v_add_u32_e32 v179, v50, v62
	v_add_u32_e32 v193, v50, v128
	v_add_u32_e32 v194, v49, v130
	v_add_u32_e32 v195, v50, v131
	v_add_u32_e32 v196, v49, v133
	v_add_u32_e32 v197, v50, v134
	v_add_u32_e32 v198, v49, v146
	v_add_u32_e32 v199, v50, v147
	v_add_u32_e32 v200, v49, v148
	v_add_u32_e32 v201, v50, v149
	v_add_u32_e32 v202, v49, v162
	v_add_u32_e32 v203, v50, v163
	v_add_u32_e32 v204, v49, v204
	v_add_u32_e32 v205, v50, v205
	v_add_u32_e32 v206, v51, v206
	v_add_u32_e32 v207, v51, v207
	v_add_u32_e32 v208, v51, v208
	v_add_u32_e32 v209, v51, v63
	v_add_u32_e32 v210, v51, v210
	v_add_u32_e32 v211, v51, v211
	v_add_u32_e32 v212, v51, v212
	v_add_u32_e32 v216, v51, v129
	v_add_u32_e32 v217, v51, v132
	v_add_u32_e32 v218, v51, v135
	v_add_u32_e32 v219, v51, v219
	v_add_u32_e32 v220, v51, v220
	v_add_u32_e32 v221, v51, v221
	v_mov_b64_e32 v[112:113], v[64:65]
	v_mov_b64_e32 v[116:117], v[64:65]
	v_mov_b64_e32 v[120:121], v[64:65]
	v_mov_b64_e32 v[124:125], v[64:65]
	s_mov_b32 s46, 0
	s_mov_b32 s29, 0
	v_lshrrev_b32_e32 v32, 8, v167
	v_mul_u32_u24_e32 v33, 0x3600, v32
	v_add_u32_e32 v168, v168, v33
	v_add_u32_e32 v169, v169, v33
	v_add_u32_e32 v170, v170, v33
	v_add_u32_e32 v171, v171, v33
	v_add_u32_e32 v169, 0xffffee00, v169
	v_add_u32_e32 v170, 0xffffdc00, v170
	v_add_u32_e32 v171, 0xffffca00, v171
	v_mul_u32_u24_e32 v66, 0x60000, v32
	v_mov_b32_e32 v67, 0
	v_lshl_add_u64 v[142:143], v[66:67], 0, v[142:143]
	v_lshl_add_u64 v[252:253], v[66:67], 0, v[252:253]
	v_lshl_add_u64 v[154:155], v[66:67], 0, v[154:155]
	v_lshl_add_u64 v[150:151], v[66:67], 0, v[150:151]
	s_mov_b32 s19, -1
	s_mov_b32 s18, 0xfffe0000
	v_lshl_add_u64 v[252:253], v[252:253], 0, s[18:19]
	s_mov_b32 s18, 0xfffc0000
	v_lshl_add_u64 v[154:155], v[154:155], 0, s[18:19]
	s_mov_b32 s18, 0xfffa0000
	v_lshl_add_u64 v[150:151], v[150:151], 0, s[18:19]
	v_mul_u32_u24_e32 v33, 0x1400, v32
	v_add_u32_e32 v164, v164, v33
	v_add_u32_e32 v152, v152, v33
	v_add_u32_e32 v152, 0xffffec00, v152
	v_lshlrev_b32_e32 v33, 6, v32
	v_add_u32_e32 v140, v140, v33
	v_add_u32_e32 v138, v138, v33
	v_add_u32_e32 v138, 0xffffffc0, v138
	v_lshrrev_b32_e32 v33, 6, v167
	s_nop 1
	v_readfirstlane_b32 s18, v33
	s_lshl_b32 s19, s18, 6
	s_sub_i32 s19, s19, 0xe0
	s_mul_i32 s20, s19, 0x110
	v_add_u32_e32 v172, s20, v172
	v_add_u32_e32 v174, s20, v174
	v_add_u32_e32 v176, s20, v176
	v_add_u32_e32 v178, s20, v178
	v_add_u32_e32 v180, s20, v180
	v_add_u32_e32 v182, s20, v182
	v_add_u32_e32 v184, s20, v184
	v_add_u32_e32 v186, s20, v186
	v_add_u32_e32 v188, s20, v188
	v_add_u32_e32 v190, s20, v190
	v_add_u32_e32 v192, s20, v192
	v_add_u32_e32 v194, s20, v194
	v_add_u32_e32 v196, s20, v196
; #define LAS __attribute__((address_space(3)))
; template <int dir>
; __device__ __forceinline__ void lru_pass(LAS unsigned char* lds, const Params& P, int b, int h, int q, bool dry) {
;     ...
;         for (int sc = 0; sc < 9; ++sc) {
;             const bool isctx = (sc == 0);
;             const int t0 = cur.t0;
; #pragma unroll
;             for (int j = 0; j < 11; ++j) { if (j != 0 && j < 9) continue;
;                 const int t = t0 + tr * 8 - 1 + j; if (t < 0 || t >= cur.L) rows[j] = (u32x4){0u, 0u, 0u, 0u}; }
;             f32x2 cw2[4][4], cb2[4];
; #pragma unroll
;             for (int k = 0; k < 5; ++k) { const f32x4 a = *(const LAS f32x4*)(CWL + k * 128 + cgp * 8), c2 = *(const LAS f32x4*)(CWL + k * 128 + cgp * 8 + 4);
;                 if (k < 4) { cw2[k][0] = (f32x2){a[0], a[1]}; cw2[k][1] = (f32x2){a[2], a[3]}; cw2[k][2] = (f32x2){c2[0], c2[1]}; cw2[k][3] = (f32x2){c2[2], c2[3]}; }
;                 else { cb2[0] = (f32x2){a[0], a[1]}; cb2[1] = (f32x2){a[2], a[3]}; cb2[2] = (f32x2){c2[0], c2[1]}; cb2[3] = (f32x2){c2[2], c2[3]}; } }
; #pragma unroll
;             for (int j = 0; j < 8; ++j) {
;                 f32x2 o0 = cb2[0], o1 = cb2[1], o2 = cb2[2], o3 = cb2[3];
; #pragma unroll
;                 for (int k = 0; k < 4; ++k) { const u32x4 rr = rows[j + k];
;                     o0 = cw2[k][0] * (f32x2){bf_lo(rr.x), bf_hi(rr.x)} + o0; o1 = cw2[k][1] * (f32x2){bf_lo(rr.y), bf_hi(rr.y)} + o1;
;                     o2 = cw2[k][2] * (f32x2){bf_lo(rr.z), bf_hi(rr.z)} + o2; o3 = cw2[k][3] * (f32x2){bf_lo(rr.w), bf_hi(rr.w)} + o3; }
;                 u32x4 w; w.x = cvt_pk_bf16(o0[0], o0[1]); w.y = cvt_pk_bf16(o1[0], o1[1]); w.z = cvt_pk_bf16(o2[0], o2[1]); w.w = cvt_pk_bf16(o3[0], o3[1]);
;                 *(LAS u32x4*)(XC + (tr * 8 + j) * XC_PITCH + cgp * 16) = w;
;             }
;     ...
;             const float Po = __shfl_xor(Pp, 32), Eo = __shfl_xor(E, 32);
;             const float P0 = g ? Po : Pp, E0 = g ? Eo : E, P1 = g ? Pp : Po, E1 = g ? E : Eo;
;             if (g == 0) { AGG[(wid * 2 + 0) * 32 + nl] = P0 * P1; AGG[(wid * 2 + 1) * 32 + nl] = fmaf(P1, E0, E1); }
;             LDS_BARRIER();
;             float cin = carry, cend = carry;
; #pragma unroll
;             for (int w = 0; w < 8; ++w) { const float pw = AGG[(w * 2 + 0) * 32 + nl], ew = AGG[(w * 2 + 1) * 32 + nl]; if (w == wid) cin = cend; cend = fmaf(pw, cend, ew); }
	v_add_u32_e32 v198, s20, v198
	v_add_u32_e32 v200, s20, v200
	v_add_u32_e32 v202, s20, v202
	v_add_u32_e32 v204, s20, v204
	s_mul_i32 s20, s19, 0x90
	v_add_u32_e32 v175, s20, v175
	v_add_u32_e32 v177, s20, v177
	v_add_u32_e32 v179, s20, v179
	v_add_u32_e32 v181, s20, v181
	v_add_u32_e32 v183, s20, v183
	v_add_u32_e32 v185, s20, v185
	v_add_u32_e32 v187, s20, v187
	v_add_u32_e32 v189, s20, v189
	v_add_u32_e32 v191, s20, v191
	v_add_u32_e32 v193, s20, v193
	v_add_u32_e32 v195, s20, v195
	v_add_u32_e32 v197, s20, v197
	v_add_u32_e32 v199, s20, v199
	v_add_u32_e32 v201, s20, v201
	v_add_u32_e32 v203, s20, v203
	v_add_u32_e32 v205, s20, v205
	s_mul_i32 s20, s19, 0x50
	v_add_u32_e32 v206, s20, v206
	v_add_u32_e32 v207, s20, v207
	v_add_u32_e32 v208, s20, v208
	v_add_u32_e32 v209, s20, v209
	v_add_u32_e32 v210, s20, v210
	v_add_u32_e32 v211, s20, v211
	v_add_u32_e32 v212, s20, v212
	v_add_u32_e32 v213, s20, v213
	v_add_u32_e32 v214, s20, v214
	v_add_u32_e32 v215, s20, v215
	v_add_u32_e32 v216, s20, v216
	v_add_u32_e32 v217, s20, v217
	v_add_u32_e32 v218, s20, v218
	v_add_u32_e32 v219, s20, v219
	v_add_u32_e32 v220, s20, v220
	v_add_u32_e32 v221, s20, v221
	s_lshl_b32 s20, s18, 1
	s_sub_i32 s20, 7, s20
	s_lshl_b32 s20, s20, 8
	v_add_u32_e32 v254, s20, v254
	s_sub_i32 s18, 7, s18
	s_lshr_b32 s101, s18, 2
	s_or_b32 s19, s18, 4
	s_cmp_eq_u32 s19, 7
	s_cselect_b64 s[0:1], -1, 0
	s_cmp_eq_u32 s19, 6
	s_cselect_b64 s[16:17], -1, 0
	s_cmp_eq_u32 s19, 5
	s_cselect_b64 s[4:5], -1, 0
	s_cmp_eq_u32 s19, 4
	s_cselect_b64 s[8:9], -1, 0
	s_cmp_eq_u32 s19, 3
	s_cselect_b64 s[10:11], -1, 0
	s_cmp_eq_u32 s19, 2
	s_cselect_b64 s[12:13], -1, 0
	s_cmp_eq_u32 s19, 1
	s_cselect_b64 s[14:15], -1, 0
	s_mov_b32 s98, 0
	s_cmp_eq_u32 s101, 0
	s_cselect_b32 s99, 0x14400, 0
	s_cselect_b32 s100, 0, 0x400
	v_add_u32_e32 v33, 0x14000, v254
	v_mov_b32_e32 v66, 1.0
	v_mov_b32_e32 v67, 0
	ds_write2_b32 v33, v66, v67 offset1:32
	s_cmp_eq_u32 s101, 0
	s_cbranch_scc1 .Lpp_b_nox
	s_waitcnt lgkmcnt(0)
	s_barrier
.Lpp_b_nox:
.LBB0_306:
	v_add_u32_e32 v32, s29, v160
	v_cmp_lt_i32_e64 s[18:19], -1, v32
	v_cmp_gt_i32_e64 s[20:21], s28, v32
	s_and_b64 s[18:19], s[18:19], s[20:21]
	v_add_u32_e32 v33, 9, v32
	s_waitcnt vmcnt(10)
	v_cndmask_b32_e64 v71, 0, v71, s[18:19]
	v_cndmask_b32_e64 v70, 0, v70, s[18:19]
	v_cndmask_b32_e64 v69, 0, v69, s[18:19]
	v_cndmask_b32_e64 v68, 0, v68, s[18:19]
	v_cmp_lt_i32_e64 s[18:19], -10, v32
	v_cmp_gt_i32_e64 s[20:21], s28, v33
	s_and_b64 s[18:19], s[18:19], s[20:21]
	v_add_u32_e32 v33, 10, v32
	s_waitcnt vmcnt(1)
	v_cndmask_b32_e64 v107, 0, v107, s[18:19]
	v_cndmask_b32_e64 v106, 0, v106, s[18:19]
	v_cndmask_b32_e64 v105, 0, v105, s[18:19]
	v_cndmask_b32_e64 v104, 0, v104, s[18:19]
	v_cmp_lt_i32_e64 s[18:19], -11, v32
	v_cmp_gt_i32_e64 s[20:21], s28, v33
	ds_read_b128 v[60:63], v165
	ds_read_b128 v[52:55], v165 offset:16
	ds_read_b128 v[44:47], v165 offset:528
	ds_read_b128 v[56:59], v165 offset:512
	ds_read_b128 v[40:43], v165 offset:1040
	ds_read_b128 v[48:51], v165 offset:1024
	ds_read_b128 v[128:131], v165 offset:2064
	ds_read_b128 v[132:135], v165 offset:2048
	ds_read_b128 v[32:35], v165 offset:1552
	ds_read_b128 v[36:39], v165 offset:1536
	v_lshlrev_b32_e32 v66, 16, v68
	v_and_b32_e32 v67, 0xffff0000, v68
	v_lshlrev_b32_e32 v148, 16, v70
	v_and_b32_e32 v149, 0xffff0000, v70
	s_waitcnt lgkmcnt(2)
	v_pk_fma_f32 v[66:67], v[60:61], v[66:67], v[132:133]
	v_lshlrev_b32_e32 v146, 16, v69
	v_and_b32_e32 v147, 0xffff0000, v69
	v_pk_fma_f32 v[148:149], v[52:53], v[148:149], v[128:129]
	v_lshlrev_b32_e32 v224, 16, v71
	v_and_b32_e32 v225, 0xffff0000, v71
	v_lshlrev_b32_e32 v228, 16, v72
	v_and_b32_e32 v229, 0xffff0000, v72
	v_lshlrev_b32_e32 v232, 16, v74
	v_and_b32_e32 v233, 0xffff0000, v74
	v_pk_fma_f32 v[146:147], v[62:63], v[146:147], v[134:135]
	v_pk_fma_f32 v[224:225], v[54:55], v[224:225], v[130:131]
	v_pk_fma_f32 v[66:67], v[56:57], v[228:229], v[66:67]
	v_lshlrev_b32_e32 v230, 16, v73
	v_and_b32_e32 v231, 0xffff0000, v73
	v_pk_fma_f32 v[148:149], v[44:45], v[232:233], v[148:149]
	v_lshlrev_b32_e32 v234, 16, v75
	v_and_b32_e32 v235, 0xffff0000, v75
	v_lshlrev_b32_e32 v236, 16, v76
	v_and_b32_e32 v237, 0xffff0000, v76
	v_lshlrev_b32_e32 v240, 16, v78
	v_and_b32_e32 v241, 0xffff0000, v78
	v_pk_fma_f32 v[146:147], v[58:59], v[230:231], v[146:147]
	v_pk_fma_f32 v[224:225], v[46:47], v[234:235], v[224:225]
	v_pk_fma_f32 v[66:67], v[48:49], v[236:237], v[66:67]
	v_lshlrev_b32_e32 v238, 16, v77
	v_and_b32_e32 v239, 0xffff0000, v77
	v_pk_fma_f32 v[148:149], v[40:41], v[240:241], v[148:149]
	v_lshlrev_b32_e32 v242, 16, v79
	v_and_b32_e32 v243, 0xffff0000, v79
	v_lshlrev_b32_e32 v244, 16, v80
	v_and_b32_e32 v245, 0xffff0000, v80
	v_lshlrev_b32_e32 v248, 16, v82
	v_and_b32_e32 v249, 0xffff0000, v82
	v_pk_fma_f32 v[146:147], v[50:51], v[238:239], v[146:147]
	v_pk_fma_f32 v[224:225], v[42:43], v[242:243], v[224:225]
	s_waitcnt lgkmcnt(0)
; #define LAS __attribute__((address_space(3)))
; __device__ __forceinline__ unsigned cvt_pk_bf16(float lo, float hi) { unsigned r; asm volatile("v_cvt_pk_bf16_f32 %0, %1, %2" : "=v"(r) : "v"(lo), "v"(hi)); return r; }
; __device__ __forceinline__ float bf_lo(unsigned u) { return __uint_as_float(u << 16); }
; __device__ __forceinline__ float bf_hi(unsigned u) { return __uint_as_float(u & 0xffff0000u); }
; template <int dir>
; __device__ __forceinline__ void lru_pass(LAS unsigned char* lds, const Params& P, int b, int h, int q, bool dry) {
;     ...
; #pragma unroll
;             for (int j = 0; j < 8; ++j) {
;                 f32x2 o0 = cb2[0], o1 = cb2[1], o2 = cb2[2], o3 = cb2[3];
; #pragma unroll
;                 for (int k = 0; k < 4; ++k) { const u32x4 rr = rows[j + k];
;                     o0 = cw2[k][0] * (f32x2){bf_lo(rr.x), bf_hi(rr.x)} + o0; o1 = cw2[k][1] * (f32x2){bf_lo(rr.y), bf_hi(rr.y)} + o1;
;                     o2 = cw2[k][2] * (f32x2){bf_lo(rr.z), bf_hi(rr.z)} + o2; o3 = cw2[k][3] * (f32x2){bf_lo(rr.w), bf_hi(rr.w)} + o3; }
;                 u32x4 w; w.x = cvt_pk_bf16(o0[0], o0[1]); w.y = cvt_pk_bf16(o1[0], o1[1]); w.z = cvt_pk_bf16(o2[0], o2[1]); w.w = cvt_pk_bf16(o3[0], o3[1]);
;                 *(LAS u32x4*)(XC + (tr * 8 + j) * XC_PITCH + cgp * 16) = w;
;             }
	v_pk_fma_f32 v[66:67], v[36:37], v[244:245], v[66:67]
	v_lshlrev_b32_e32 v246, 16, v81
	v_and_b32_e32 v247, 0xffff0000, v81
	v_pk_fma_f32 v[148:149], v[32:33], v[248:249], v[148:149]
	v_lshlrev_b32_e32 v250, 16, v83
	v_and_b32_e32 v251, 0xffff0000, v83
	v_pk_fma_f32 v[146:147], v[38:39], v[246:247], v[146:147]
	v_pk_fma_f32 v[162:163], v[34:35], v[250:251], v[224:225]
	v_cvt_pk_bf16_f32 v224, v66, v67
	v_cvt_pk_bf16_f32 v225, v146, v147
	v_cvt_pk_bf16_f32 v226, v148, v149
	v_pk_fma_f32 v[66:67], v[60:61], v[228:229], v[132:133]
	v_pk_fma_f32 v[148:149], v[52:53], v[232:233], v[128:129]
	v_pk_fma_f32 v[146:147], v[62:63], v[230:231], v[134:135]
	v_pk_fma_f32 v[66:67], v[56:57], v[236:237], v[66:67]
	v_pk_fma_f32 v[148:149], v[44:45], v[240:241], v[148:149]
	v_pk_fma_f32 v[146:147], v[58:59], v[238:239], v[146:147]
	v_pk_fma_f32 v[66:67], v[48:49], v[244:245], v[66:67]
	v_pk_fma_f32 v[148:149], v[40:41], v[248:249], v[148:149]
	v_lshlrev_b32_e32 v228, 16, v84
	v_and_b32_e32 v229, 0xffff0000, v84
	v_lshlrev_b32_e32 v232, 16, v86
	v_and_b32_e32 v233, 0xffff0000, v86
	v_cvt_pk_bf16_f32 v227, v162, v163
	v_pk_fma_f32 v[162:163], v[54:55], v[234:235], v[130:131]
	v_pk_fma_f32 v[146:147], v[50:51], v[246:247], v[146:147]
	v_pk_fma_f32 v[66:67], v[36:37], v[228:229], v[66:67]
	v_lshlrev_b32_e32 v230, 16, v85
	v_and_b32_e32 v231, 0xffff0000, v85
	v_pk_fma_f32 v[148:149], v[32:33], v[232:233], v[148:149]
	ds_write_b128 v166, v[224:227]
	v_pk_fma_f32 v[162:163], v[46:47], v[242:243], v[162:163]
	v_pk_fma_f32 v[146:147], v[38:39], v[230:231], v[146:147]
	v_cvt_pk_bf16_f32 v224, v66, v67
	v_pk_fma_f32 v[66:67], v[60:61], v[236:237], v[132:133]
	v_cvt_pk_bf16_f32 v225, v146, v147
	v_cvt_pk_bf16_f32 v226, v148, v149
	v_pk_fma_f32 v[148:149], v[52:53], v[240:241], v[128:129]
	v_pk_fma_f32 v[162:163], v[42:43], v[250:251], v[162:163]
	v_lshlrev_b32_e32 v234, 16, v87
	v_and_b32_e32 v235, 0xffff0000, v87
	v_pk_fma_f32 v[146:147], v[62:63], v[238:239], v[134:135]
	v_pk_fma_f32 v[66:67], v[56:57], v[244:245], v[66:67]
	v_pk_fma_f32 v[148:149], v[44:45], v[248:249], v[148:149]
	v_pk_fma_f32 v[162:163], v[34:35], v[234:235], v[162:163]
	v_pk_fma_f32 v[146:147], v[58:59], v[246:247], v[146:147]
	v_pk_fma_f32 v[66:67], v[48:49], v[228:229], v[66:67]
	v_pk_fma_f32 v[148:149], v[40:41], v[232:233], v[148:149]
	v_lshlrev_b32_e32 v236, 16, v88
	v_and_b32_e32 v237, 0xffff0000, v88
	v_lshlrev_b32_e32 v240, 16, v90
	v_and_b32_e32 v241, 0xffff0000, v90
	v_cvt_pk_bf16_f32 v227, v162, v163
	v_pk_fma_f32 v[162:163], v[54:55], v[242:243], v[130:131]
	v_pk_fma_f32 v[146:147], v[50:51], v[230:231], v[146:147]
	v_pk_fma_f32 v[66:67], v[36:37], v[236:237], v[66:67]
	v_lshlrev_b32_e32 v238, 16, v89
	v_and_b32_e32 v239, 0xffff0000, v89
	v_pk_fma_f32 v[148:149], v[32:33], v[240:241], v[148:149]
	ds_write_b128 v166, v[224:227] offset:272
	v_pk_fma_f32 v[162:163], v[46:47], v[250:251], v[162:163]
	v_pk_fma_f32 v[146:147], v[38:39], v[238:239], v[146:147]
	v_cvt_pk_bf16_f32 v224, v66, v67
	v_pk_fma_f32 v[66:67], v[60:61], v[244:245], v[132:133]
	v_cvt_pk_bf16_f32 v225, v146, v147
	v_cvt_pk_bf16_f32 v226, v148, v149
	v_pk_fma_f32 v[148:149], v[52:53], v[248:249], v[128:129]
	v_pk_fma_f32 v[162:163], v[42:43], v[234:235], v[162:163]
	v_lshlrev_b32_e32 v242, 16, v91
	v_and_b32_e32 v243, 0xffff0000, v91
	v_pk_fma_f32 v[146:147], v[62:63], v[246:247], v[134:135]
	v_pk_fma_f32 v[66:67], v[56:57], v[228:229], v[66:67]
	v_pk_fma_f32 v[148:149], v[44:45], v[232:233], v[148:149]
	v_pk_fma_f32 v[162:163], v[34:35], v[242:243], v[162:163]
	v_pk_fma_f32 v[146:147], v[58:59], v[230:231], v[146:147]
	v_pk_fma_f32 v[66:67], v[48:49], v[236:237], v[66:67]
	v_pk_fma_f32 v[148:149], v[40:41], v[240:241], v[148:149]
	v_lshlrev_b32_e32 v244, 16, v92
	v_and_b32_e32 v245, 0xffff0000, v92
	v_lshlrev_b32_e32 v248, 16, v94
	v_and_b32_e32 v249, 0xffff0000, v94
	v_cvt_pk_bf16_f32 v227, v162, v163
	v_pk_fma_f32 v[162:163], v[54:55], v[250:251], v[130:131]
	v_pk_fma_f32 v[146:147], v[50:51], v[238:239], v[146:147]
	v_pk_fma_f32 v[66:67], v[36:37], v[244:245], v[66:67]
	v_lshlrev_b32_e32 v246, 16, v93
	v_and_b32_e32 v247, 0xffff0000, v93
	v_pk_fma_f32 v[148:149], v[32:33], v[248:249], v[148:149]
	ds_write_b128 v166, v[224:227] offset:544
	v_pk_fma_f32 v[162:163], v[46:47], v[234:235], v[162:163]
	v_pk_fma_f32 v[146:147], v[38:39], v[246:247], v[146:147]
	v_cvt_pk_bf16_f32 v224, v66, v67
	v_pk_fma_f32 v[66:67], v[60:61], v[228:229], v[132:133]
	v_cvt_pk_bf16_f32 v225, v146, v147
	v_cvt_pk_bf16_f32 v226, v148, v149
	v_pk_fma_f32 v[148:149], v[52:53], v[232:233], v[128:129]
	v_pk_fma_f32 v[162:163], v[42:43], v[242:243], v[162:163]
	v_lshlrev_b32_e32 v250, 16, v95
	v_and_b32_e32 v251, 0xffff0000, v95
	v_pk_fma_f32 v[146:147], v[62:63], v[230:231], v[134:135]
	v_pk_fma_f32 v[66:67], v[56:57], v[236:237], v[66:67]
	v_pk_fma_f32 v[148:149], v[44:45], v[240:241], v[148:149]
	v_pk_fma_f32 v[162:163], v[34:35], v[250:251], v[162:163]
	v_pk_fma_f32 v[146:147], v[58:59], v[238:239], v[146:147]
	v_pk_fma_f32 v[66:67], v[48:49], v[244:245], v[66:67]
	v_pk_fma_f32 v[148:149], v[40:41], v[248:249], v[148:149]
	v_lshlrev_b32_e32 v228, 16, v96
	v_and_b32_e32 v229, 0xffff0000, v96
	v_lshlrev_b32_e32 v232, 16, v98
	v_and_b32_e32 v233, 0xffff0000, v98
	v_cvt_pk_bf16_f32 v227, v162, v163
	v_pk_fma_f32 v[162:163], v[54:55], v[234:235], v[130:131]
	v_pk_fma_f32 v[146:147], v[50:51], v[246:247], v[146:147]
	v_pk_fma_f32 v[66:67], v[36:37], v[228:229], v[66:67]
	v_lshlrev_b32_e32 v230, 16, v97
	v_and_b32_e32 v231, 0xffff0000, v97
	v_pk_fma_f32 v[148:149], v[32:33], v[232:233], v[148:149]
	ds_write_b128 v166, v[224:227] offset:816
; #define LAS __attribute__((address_space(3)))
; __device__ __forceinline__ unsigned cvt_pk_bf16(float lo, float hi) { unsigned r; asm volatile("v_cvt_pk_bf16_f32 %0, %1, %2" : "=v"(r) : "v"(lo), "v"(hi)); return r; }
; __device__ __forceinline__ float bf_lo(unsigned u) { return __uint_as_float(u << 16); }
; __device__ __forceinline__ float bf_hi(unsigned u) { return __uint_as_float(u & 0xffff0000u); }
; template <int dir>
; __device__ __forceinline__ void lru_pass(LAS unsigned char* lds, const Params& P, int b, int h, int q, bool dry) {
;     ...
; #pragma unroll
;             for (int j = 0; j < 8; ++j) {
;                 f32x2 o0 = cb2[0], o1 = cb2[1], o2 = cb2[2], o3 = cb2[3];
; #pragma unroll
;                 for (int k = 0; k < 4; ++k) { const u32x4 rr = rows[j + k];
;                     o0 = cw2[k][0] * (f32x2){bf_lo(rr.x), bf_hi(rr.x)} + o0; o1 = cw2[k][1] * (f32x2){bf_lo(rr.y), bf_hi(rr.y)} + o1;
;                     o2 = cw2[k][2] * (f32x2){bf_lo(rr.z), bf_hi(rr.z)} + o2; o3 = cw2[k][3] * (f32x2){bf_lo(rr.w), bf_hi(rr.w)} + o3; }
;                 u32x4 w; w.x = cvt_pk_bf16(o0[0], o0[1]); w.y = cvt_pk_bf16(o1[0], o1[1]); w.z = cvt_pk_bf16(o2[0], o2[1]); w.w = cvt_pk_bf16(o3[0], o3[1]);
;                 *(LAS u32x4*)(XC + (tr * 8 + j) * XC_PITCH + cgp * 16) = w;
;             }
; #pragma unroll
;             for (int i = 0; i < NIN; ++i) { const int id = tid + i * NTHREADS;
;                 if (dir == 0) *(LAS u32x4*)(TIN + (id >> 2) * IO_NP + (id & 3) * 16) = inr[i];
;                 else *(LAS u32x4*)(TIN + (id >> 3) * IO_WP + (id & 7) * 16) = inr[i]; }
;             LruTile nxt = cur;
;             if (sc < 8) { nxt = lru_tile(Z, ZC, b, h, dir, sc + 1); lru_load_rows(rows, nxt, tr, cgp);
; #pragma unroll
;                 for (int i = 0; i < NIN; ++i) { const int id = tid + i * NTHREADS;
;                     if (dir == 0) inr[i] = *(const u32x4*)(Zg + (size_t)(nxt.t0 + (id >> 2)) * 128 + (id & 3) * 8);
;                     else inr[i] = *(const u32x4*)(Hg + (size_t)(nxt.t0 + (id >> 3)) * DM + (id & 7) * 4); } }
	v_pk_fma_f32 v[162:163], v[46:47], v[242:243], v[162:163]
	v_pk_fma_f32 v[146:147], v[38:39], v[230:231], v[146:147]
	v_cvt_pk_bf16_f32 v224, v66, v67
	v_pk_fma_f32 v[66:67], v[60:61], v[236:237], v[132:133]
	v_cvt_pk_bf16_f32 v225, v146, v147
	v_cvt_pk_bf16_f32 v226, v148, v149
	v_pk_fma_f32 v[148:149], v[52:53], v[240:241], v[128:129]
	v_pk_fma_f32 v[162:163], v[42:43], v[250:251], v[162:163]
	v_lshlrev_b32_e32 v234, 16, v99
	v_and_b32_e32 v235, 0xffff0000, v99
	v_pk_fma_f32 v[146:147], v[62:63], v[238:239], v[134:135]
	v_pk_fma_f32 v[66:67], v[56:57], v[244:245], v[66:67]
	v_pk_fma_f32 v[148:149], v[44:45], v[248:249], v[148:149]
	v_pk_fma_f32 v[162:163], v[34:35], v[234:235], v[162:163]
	v_pk_fma_f32 v[146:147], v[58:59], v[246:247], v[146:147]
	v_pk_fma_f32 v[66:67], v[48:49], v[228:229], v[66:67]
	v_pk_fma_f32 v[148:149], v[40:41], v[232:233], v[148:149]
	v_lshlrev_b32_e32 v236, 16, v100
	v_and_b32_e32 v237, 0xffff0000, v100
	v_lshlrev_b32_e32 v240, 16, v102
	v_and_b32_e32 v241, 0xffff0000, v102
	v_cvt_pk_bf16_f32 v227, v162, v163
	v_pk_fma_f32 v[162:163], v[54:55], v[242:243], v[130:131]
	v_pk_fma_f32 v[146:147], v[50:51], v[230:231], v[146:147]
	v_pk_fma_f32 v[66:67], v[36:37], v[236:237], v[66:67]
	v_lshlrev_b32_e32 v238, 16, v101
	v_and_b32_e32 v239, 0xffff0000, v101
	v_pk_fma_f32 v[148:149], v[32:33], v[240:241], v[148:149]
	s_and_b64 s[18:19], s[18:19], s[20:21]
	ds_write_b128 v166, v[224:227] offset:1088
	v_pk_fma_f32 v[162:163], v[46:47], v[250:251], v[162:163]
	v_pk_fma_f32 v[146:147], v[38:39], v[238:239], v[146:147]
	v_cvt_pk_bf16_f32 v224, v66, v67
	v_pk_fma_f32 v[66:67], v[60:61], v[244:245], v[132:133]
	v_cvt_pk_bf16_f32 v225, v146, v147
	v_cvt_pk_bf16_f32 v226, v148, v149
	v_pk_fma_f32 v[148:149], v[52:53], v[248:249], v[128:129]
	v_pk_fma_f32 v[60:61], v[60:61], v[228:229], v[132:133]
	v_pk_fma_f32 v[52:53], v[52:53], v[232:233], v[128:129]
	s_waitcnt vmcnt(0)
	v_cndmask_b32_e64 v108, 0, v108, s[18:19]
	v_pk_fma_f32 v[162:163], v[42:43], v[234:235], v[162:163]
	v_lshlrev_b32_e32 v242, 16, v103
	v_and_b32_e32 v243, 0xffff0000, v103
	v_pk_fma_f32 v[146:147], v[62:63], v[246:247], v[134:135]
	v_pk_fma_f32 v[66:67], v[56:57], v[228:229], v[66:67]
	v_pk_fma_f32 v[148:149], v[44:45], v[232:233], v[148:149]
	v_lshlrev_b32_e32 v244, 16, v104
	v_and_b32_e32 v245, 0xffff0000, v104
	v_lshlrev_b32_e32 v248, 16, v106
	v_and_b32_e32 v249, 0xffff0000, v106
	v_pk_fma_f32 v[62:63], v[62:63], v[230:231], v[134:135]
	v_pk_fma_f32 v[56:57], v[56:57], v[236:237], v[60:61]
	v_pk_fma_f32 v[44:45], v[44:45], v[240:241], v[52:53]
	v_cndmask_b32_e64 v109, 0, v109, s[18:19]
	v_pk_fma_f32 v[162:163], v[34:35], v[242:243], v[162:163]
	v_pk_fma_f32 v[146:147], v[58:59], v[230:231], v[146:147]
	v_pk_fma_f32 v[66:67], v[48:49], v[236:237], v[66:67]
	v_pk_fma_f32 v[148:149], v[40:41], v[240:241], v[148:149]
	v_lshlrev_b32_e32 v246, 16, v105
	v_and_b32_e32 v247, 0xffff0000, v105
	v_pk_fma_f32 v[58:59], v[58:59], v[238:239], v[62:63]
	v_pk_fma_f32 v[48:49], v[48:49], v[244:245], v[56:57]
	v_pk_fma_f32 v[40:41], v[40:41], v[248:249], v[44:45]
	v_lshlrev_b32_e32 v44, 16, v108
	v_and_b32_e32 v45, 0xffff0000, v108
	v_cndmask_b32_e64 v110, 0, v110, s[18:19]
	v_cvt_pk_bf16_f32 v227, v162, v163
	v_pk_fma_f32 v[162:163], v[54:55], v[250:251], v[130:131]
	v_pk_fma_f32 v[146:147], v[50:51], v[238:239], v[146:147]
	v_pk_fma_f32 v[66:67], v[36:37], v[244:245], v[66:67]
	v_pk_fma_f32 v[54:55], v[54:55], v[234:235], v[130:131]
	v_pk_fma_f32 v[50:51], v[50:51], v[246:247], v[58:59]
	v_pk_fma_f32 v[36:37], v[36:37], v[44:45], v[48:49]
	v_lshlrev_b32_e32 v44, 16, v109
	v_and_b32_e32 v45, 0xffff0000, v109
	v_cndmask_b32_e64 v111, 0, v111, s[18:19]
	v_pk_fma_f32 v[162:163], v[46:47], v[234:235], v[162:163]
	v_pk_fma_f32 v[146:147], v[38:39], v[246:247], v[146:147]
	v_lshlrev_b32_e32 v250, 16, v107
	v_and_b32_e32 v251, 0xffff0000, v107
	v_pk_fma_f32 v[46:47], v[46:47], v[242:243], v[54:55]
	v_pk_fma_f32 v[38:39], v[38:39], v[44:45], v[50:51]
	v_lshlrev_b32_e32 v44, 16, v110
	v_and_b32_e32 v45, 0xffff0000, v110
	v_pk_fma_f32 v[162:163], v[42:43], v[242:243], v[162:163]
	v_pk_fma_f32 v[148:149], v[32:33], v[248:249], v[148:149]
	v_pk_fma_f32 v[42:43], v[42:43], v[250:251], v[46:47]
	v_pk_fma_f32 v[40:41], v[32:33], v[44:45], v[40:41]
	v_lshlrev_b32_e32 v32, 16, v111
	v_and_b32_e32 v33, 0xffff0000, v111
	ds_write_b128 v166, v[224:227] offset:1360
	v_pk_fma_f32 v[162:163], v[34:35], v[250:251], v[162:163]
	v_cvt_pk_bf16_f32 v224, v66, v67
	v_cvt_pk_bf16_f32 v225, v146, v147
	v_cvt_pk_bf16_f32 v226, v148, v149
	v_pk_fma_f32 v[42:43], v[34:35], v[32:33], v[42:43]
	v_cvt_pk_bf16_f32 v227, v162, v163
	ds_write_b128 v166, v[224:227] offset:1632
	v_cvt_pk_bf16_f32 v32, v36, v37
	v_cvt_pk_bf16_f32 v33, v38, v39
	v_cvt_pk_bf16_f32 v34, v40, v41
	v_cvt_pk_bf16_f32 v35, v42, v43
	s_cmp_eq_u32 s44, 0xff800000
	ds_write_b128 v166, v[32:35] offset:1904
	ds_write_b128 v168, v[112:115]
	ds_write_b128 v169, v[116:119]
	ds_write_b128 v170, v[120:123]
	ds_write_b128 v171, v[124:127]
	s_cbranch_scc1 .LBB0_308
	global_load_dwordx4 v[68:71], v[144:145], off offset:-1280
	global_load_dwordx4 v[72:75], v[144:145], off offset:-1024
	global_load_dwordx4 v[76:79], v[144:145], off offset:-768
	global_load_dwordx4 v[80:83], v[144:145], off offset:-512
	global_load_dwordx4 v[84:87], v[144:145], off offset:-256
	global_load_dwordx4 v[88:91], v[144:145], off
	global_load_dwordx4 v[92:95], v[144:145], off offset:256
	global_load_dwordx4 v[96:99], v[144:145], off offset:512
	global_load_dwordx4 v[100:103], v[144:145], off offset:768
	global_load_dwordx4 v[104:107], v[144:145], off offset:1024
	global_load_dwordx4 v[108:111], v[144:145], off offset:1280
	v_lshl_add_u64 v[32:33], v[142:143], 0, s[44:45]
	v_lshl_add_u64 v[34:35], v[252:253], 0, s[44:45]
	global_load_dwordx4 v[112:115], v[32:33], off sc1
	global_load_dwordx4 v[116:119], v[34:35], off sc1
	v_lshl_add_u64 v[32:33], v[154:155], 0, s[44:45]
	v_lshl_add_u64 v[34:35], v[150:151], 0, s[44:45]
	global_load_dwordx4 v[120:123], v[32:33], off sc1
	global_load_dwordx4 v[124:127], v[34:35], off sc1
	s_movk_i32 s28, 0x800
	s_mov_b32 s20, s25
	s_branch .LBB0_309

; #define LAS __attribute__((address_space(3)))
; template <int dir>
; __device__ __forceinline__ void lru_pass(LAS unsigned char* lds, const Params& P, int b, int h, int q, bool dry) {
;     ...
;             f32x16 zr, zi;
; #pragma unroll
;             for (int v = 0; v < 16; ++v) { zr[v] = br; zi[v] = bi; }
;             const int sbase = 32 * wid + 16 * g;
;             { const int sl = 32 * wid + s_i; const int tlA = dir == 0 ? sl : 255 - sl;
;               const LAS unsigned char* ap = XC + tlA * XC_PITCH + 16 * g;
;               const LAS unsigned char* wrp = WB + nl * XC_PITCH + 16 * g; const LAS unsigned char* wip = wrp + 32 * XC_PITCH;
; #pragma unroll
;               for (int ks = 0; ks < 8; ++ks) { const bf16x8 A = *(const LAS bf16x8*)(ap + 32 * ks);
;                   const bf16x8 Br = *(const LAS bf16x8*)(wrp + 32 * ks), Bi = *(const LAS bf16x8*)(wip + 32 * ks);
;                   zr = __builtin_amdgcn_mfma_f32_32x32x16_bf16(A, Br, zr, 0, 0, 0); zi = __builtin_amdgcn_mfma_f32_32x32x16_bf16(A, Bi, zi, 0, 0, 0); } }
;             unsigned xcb[16], pk[16];
; #pragma unroll
;             for (int v = 0; v < 16; ++v) { const int s = sbase + v; const int tl = dir == 0 ? s : 255 - s; xcb[v] = *(const LAS bf16_t*)(XC + tl * XC_PITCH + chl * 2);
;                 if (dir == 0) pk[v] = *(const LAS bf16_t*)(TIN + tl * IO_NP + nl * 2); else pk[v] = *(const LAS unsigned*)(TIN + tl * IO_WP + nl * 4); }
;             float Pp = 1.f, E = 0.f;
; #pragma unroll
;             for (int v = 0; v < 16; ++v) {
;                 const float xcv = __uint_as_float(xcb[v] << 16);
;                 const float r = __builtin_amdgcn_rcpf(1.0f + __builtin_amdgcn_exp2f(zr[v]));
;                 const float ig = __builtin_amdgcn_rcpf(1.0f + __builtin_amdgcn_exp2f(zi[v]));
;                 const float a = __builtin_amdgcn_exp2f(cl * r);
;                 const float sq = __builtin_amdgcn_sqrtf(fmaf(-a, a, 1.0f));
;                 const float u = sq * ig * xcv;
;                 E = fmaf(a, E, u); Pp *= a; zr[v] = E; zi[v] = Pp; }
.LBB0_311:
	ds_read_b128 v[128:131], v172
	ds_read_b128 v[48:51], v173
	ds_read_b128 v[132:135], v172 offset:32
	ds_read_b128 v[52:55], v173 offset:32
	s_waitcnt lgkmcnt(2)
	v_mfma_f32_32x32x16_bf16 v[32:47], v[128:131], v[48:51], v[0:15]
	s_waitcnt lgkmcnt(0)
	v_mfma_f32_32x32x16_bf16 v[32:47], v[132:135], v[52:55], v[32:47]
	ds_read_b128 v[224:227], v172 offset:64
	ds_read_b128 v[48:51], v173 offset:64
	ds_read_b128 v[228:231], v172 offset:96
	ds_read_b128 v[52:55], v173 offset:96
	s_waitcnt lgkmcnt(2)
	v_mfma_f32_32x32x16_bf16 v[32:47], v[224:227], v[48:51], v[32:47]
	s_waitcnt lgkmcnt(0)
	v_mfma_f32_32x32x16_bf16 v[32:47], v[228:231], v[52:55], v[32:47]
	ds_read_b128 v[232:235], v172 offset:128
	ds_read_b128 v[48:51], v173 offset:128
	ds_read_b128 v[236:239], v172 offset:160
	ds_read_b128 v[52:55], v173 offset:160
	s_waitcnt lgkmcnt(2)
	v_mfma_f32_32x32x16_bf16 v[32:47], v[232:235], v[48:51], v[32:47]
	s_waitcnt lgkmcnt(0)
	v_mfma_f32_32x32x16_bf16 v[32:47], v[236:239], v[52:55], v[32:47]
	ds_read_b128 v[240:243], v172 offset:192
	ds_read_b128 v[48:51], v173 offset:192
	ds_read_b128 v[244:247], v172 offset:224
	ds_read_b128 v[52:55], v173 offset:224
	ds_read_b128 v[248:251], v173 offset:8704
	ds_read_b128 v[146:149], v173 offset:8736
	s_waitcnt lgkmcnt(4)
	v_mfma_f32_32x32x16_bf16 v[32:47], v[240:243], v[48:51], v[32:47]
	s_waitcnt lgkmcnt(2)
	v_mfma_f32_32x32x16_bf16 v[32:47], v[244:247], v[52:55], v[32:47]
	s_waitcnt lgkmcnt(1)
	v_mfma_f32_32x32x16_bf16 v[48:63], v[128:131], v[248:251], v[16:31]
	s_nop 9
	v_exp_f32_e32 v32, v32
	v_exp_f32_e32 v33, v33
	v_exp_f32_e32 v34, v34
	v_add_f32_e32 v32, 1.0, v32
	v_rcp_f32_e32 v32, v32
	v_add_f32_e32 v33, 1.0, v33
	s_waitcnt lgkmcnt(0)
	v_mfma_f32_32x32x16_bf16 v[48:63], v[132:135], v[146:149], v[48:63]
	ds_read_b128 v[128:131], v173 offset:8768
	ds_read_b128 v[132:135], v173 offset:8800
	v_mul_f32_e32 v32, v159, v32
	v_rcp_f32_e32 v33, v33
	s_nop 0
	v_mul_f32_e32 v33, v159, v33
	s_waitcnt lgkmcnt(1)
	v_mfma_f32_32x32x16_bf16 v[48:63], v[224:227], v[128:131], v[48:63]
	v_exp_f32_e32 v227, v32
	v_exp_f32_e32 v33, v33
	s_waitcnt lgkmcnt(0)
	v_mfma_f32_32x32x16_bf16 v[48:63], v[228:231], v[132:135], v[48:63]
	ds_read_b128 v[128:131], v173 offset:8832
	ds_read_b128 v[132:135], v173 offset:8864
	ds_read_b128 v[146:149], v173 offset:8896
	ds_read_b128 v[228:231], v173 offset:8928
	s_waitcnt lgkmcnt(3)
	v_mfma_f32_32x32x16_bf16 v[48:63], v[232:235], v[128:131], v[48:63]
	ds_read_u16 v162, v174
	ds_read_b32 v226, v175
	ds_read_u16 v163, v176
	ds_read_b32 v225, v177
	ds_read_u16 v232, v178
	ds_read_b32 v224, v179
	ds_read_u16 v233, v180
	ds_read_b32 v223, v181
	s_waitcnt lgkmcnt(7)
	v_lshlrev_b32_e32 v162, 16, v162
	s_waitcnt lgkmcnt(5)
	v_lshlrev_b32_e32 v163, 16, v163
	v_mfma_f32_32x32x16_bf16 v[48:63], v[236:239], v[132:135], v[48:63]
	ds_read_u16 v234, v182
	ds_read_b32 v135, v183
	ds_read_u16 v235, v184
	ds_read_b32 v134, v185
	ds_read_u16 v236, v186
	ds_read_b32 v133, v187
	ds_read_u16 v237, v188
	ds_read_b32 v131, v189
	v_mfma_f32_32x32x16_bf16 v[48:63], v[240:243], v[146:149], v[48:63]
	ds_read_u16 v146, v190
	ds_read_b32 v132, v191
	ds_read_u16 v147, v192
	ds_read_b32 v130, v193
	ds_read_u16 v148, v194
	ds_read_b32 v129, v195
	ds_read_u16 v149, v196
	ds_read_b32 v128, v197
	v_mfma_f32_32x32x16_bf16 v[48:63], v[244:247], v[228:231], v[48:63]
	s_nop 11
	v_exp_f32_e32 v228, v48
	ds_read_u16 v239, v198
	ds_read_b32 v67, v199
	ds_read_u16 v240, v200
	ds_read_b32 v66, v201
	ds_read_u16 v241, v202
	ds_read_b32 v64, v203
	ds_read_u16 v242, v204
	ds_read_b32 v48, v205
	v_add_f32_e32 v32, 1.0, v228
	v_fma_f32 v228, -v227, v227, 1.0
	v_rcp_f32_e32 v32, v32
	v_sqrt_f32_e32 v228, v228
	s_nop 0
	v_mul_f32_e32 v32, v228, v32
	v_exp_f32_e32 v228, v49
	v_mul_f32_e32 v49, v32, v162
	v_fma_f32 v162, -v33, v33, 1.0
	v_sqrt_f32_e32 v162, v162
	v_add_f32_e32 v32, 1.0, v228
	v_rcp_f32_e32 v32, v32
	v_fmac_f32_e32 v49, 0, v227
	v_mul_f32_e32 v32, v162, v32
	v_mul_f32_e32 v228, v32, v163
	v_add_f32_e32 v32, 1.0, v34
	v_rcp_f32_e32 v32, v32
	v_exp_f32_e32 v34, v50
	v_fmac_f32_e32 v228, v33, v49
	v_mul_f32_e32 v50, v227, v33
	v_mul_f32_e32 v32, v159, v32
	v_exp_f32_e32 v32, v32
	v_add_f32_e32 v33, 1.0, v34
	v_exp_f32_e32 v34, v35
	v_rcp_f32_e32 v33, v33
	v_fma_f32 v35, -v32, v32, 1.0
	v_sqrt_f32_e32 v35, v35
	v_add_f32_e32 v34, 1.0, v34
	v_rcp_f32_e32 v34, v34
	s_waitcnt lgkmcnt(14)
; template <int dir>
; __device__ __forceinline__ void lru_pass(LAS unsigned char* lds, const Params& P, int b, int h, int q, bool dry) {
;     ...
;             float Pp = 1.f, E = 0.f;
; #pragma unroll
;             for (int v = 0; v < 16; ++v) {
;                 const float xcv = __uint_as_float(xcb[v] << 16);
;                 const float r = __builtin_amdgcn_rcpf(1.0f + __builtin_amdgcn_exp2f(zr[v]));
;                 const float ig = __builtin_amdgcn_rcpf(1.0f + __builtin_amdgcn_exp2f(zi[v]));
;                 const float a = __builtin_amdgcn_exp2f(cl * r);
;                 const float sq = __builtin_amdgcn_sqrtf(fmaf(-a, a, 1.0f));
;                 const float u = sq * ig * xcv;
;                 E = fmaf(a, E, u); Pp *= a; zr[v] = E; zi[v] = Pp; }
;             const float Po = __shfl_xor(Pp, 32), Eo = __shfl_xor(E, 32);
;             const float P0 = g ? Po : Pp, E0 = g ? Eo : E, P1 = g ? Pp : Po, E1 = g ? E : Eo;
;             if (g == 0) { AGG[(wid * 2 + 0) * 32 + nl] = P0 * P1; AGG[(wid * 2 + 1) * 32 + nl] = fmaf(P1, E0, E1); }
	v_lshlrev_b32_e32 v162, 16, v232
	v_mul_f32_e32 v33, v35, v33
	v_mul_f32_e32 v229, v33, v162
	v_mul_f32_e32 v34, v159, v34
	v_exp_f32_e32 v33, v51
	v_exp_f32_e32 v34, v34
	v_fmac_f32_e32 v229, v32, v228
	v_mul_f32_e32 v51, v32, v50
	v_exp_f32_e32 v32, v36
	v_add_f32_e32 v33, 1.0, v33
	v_fma_f32 v35, -v34, v34, 1.0
	v_rcp_f32_e32 v33, v33
	v_sqrt_f32_e32 v35, v35
	v_add_f32_e32 v32, 1.0, v32
	v_rcp_f32_e32 v32, v32
	v_lshlrev_b32_e32 v36, 16, v233
	v_mul_f32_e32 v33, v35, v33
	v_mul_f32_e32 v230, v33, v36
	v_mul_f32_e32 v32, v159, v32
	v_fmac_f32_e32 v230, v34, v229
	v_exp_f32_e32 v33, v52
	v_mul_f32_e32 v52, v34, v51
	v_exp_f32_e32 v32, v32
	v_exp_f32_e32 v34, v37
	v_add_f32_e32 v33, 1.0, v33
	v_rcp_f32_e32 v33, v33
	v_fma_f32 v35, -v32, v32, 1.0
	v_add_f32_e32 v34, 1.0, v34
	v_sqrt_f32_e32 v35, v35
	v_rcp_f32_e32 v34, v34
	v_lshlrev_b32_e32 v36, 16, v234
	v_mul_f32_e32 v33, v35, v33
	v_mul_f32_e32 v34, v159, v34
	v_mul_f32_e32 v231, v33, v36
	v_exp_f32_e32 v33, v53
	v_exp_f32_e32 v34, v34
	v_fmac_f32_e32 v231, v32, v230
	v_mul_f32_e32 v53, v32, v52
	v_exp_f32_e32 v32, v38
	v_add_f32_e32 v33, 1.0, v33
	v_fma_f32 v35, -v34, v34, 1.0
	v_rcp_f32_e32 v33, v33
	v_sqrt_f32_e32 v35, v35
	v_add_f32_e32 v32, 1.0, v32
	v_rcp_f32_e32 v32, v32
	v_lshlrev_b32_e32 v36, 16, v235
	v_mul_f32_e32 v33, v35, v33
	v_mul_f32_e32 v232, v33, v36
	v_mul_f32_e32 v32, v159, v32
	v_fmac_f32_e32 v232, v34, v231
	v_exp_f32_e32 v33, v54
	v_mul_f32_e32 v54, v34, v53
	v_exp_f32_e32 v32, v32
	v_exp_f32_e32 v34, v39
	v_add_f32_e32 v33, 1.0, v33
	v_rcp_f32_e32 v33, v33
	v_fma_f32 v35, -v32, v32, 1.0
	v_add_f32_e32 v34, 1.0, v34
	v_sqrt_f32_e32 v35, v35
	v_rcp_f32_e32 v34, v34
	v_lshlrev_b32_e32 v36, 16, v236
	v_mul_f32_e32 v33, v35, v33
	v_mul_f32_e32 v34, v159, v34
	v_mul_f32_e32 v233, v33, v36
	v_exp_f32_e32 v33, v55
	v_exp_f32_e32 v34, v34
	v_fmac_f32_e32 v233, v32, v232
	v_mul_f32_e32 v55, v32, v54
	v_exp_f32_e32 v32, v40
	v_add_f32_e32 v33, 1.0, v33
	v_fma_f32 v35, -v34, v34, 1.0
	v_rcp_f32_e32 v33, v33
	v_sqrt_f32_e32 v35, v35
	v_add_f32_e32 v32, 1.0, v32
	v_rcp_f32_e32 v32, v32
	v_lshlrev_b32_e32 v36, 16, v237
	v_mul_f32_e32 v33, v35, v33
	v_mul_f32_e32 v234, v33, v36
	v_mul_f32_e32 v32, v159, v32
	v_fmac_f32_e32 v234, v34, v233
	v_exp_f32_e32 v33, v56
	v_mul_f32_e32 v56, v34, v55
	v_exp_f32_e32 v32, v32
	v_exp_f32_e32 v34, v41
	v_add_f32_e32 v33, 1.0, v33
	v_rcp_f32_e32 v33, v33
	v_fma_f32 v35, -v32, v32, 1.0
	v_add_f32_e32 v34, 1.0, v34
	v_sqrt_f32_e32 v35, v35
	v_rcp_f32_e32 v34, v34
	v_lshlrev_b32_e32 v36, 16, v146
	v_mul_f32_e32 v33, v35, v33
	v_mul_f32_e32 v34, v159, v34
	v_mul_f32_e32 v235, v33, v36
	v_exp_f32_e32 v33, v57
	v_exp_f32_e32 v34, v34
	v_fmac_f32_e32 v235, v32, v234
	v_mul_f32_e32 v57, v32, v56
	v_exp_f32_e32 v32, v42
	v_add_f32_e32 v33, 1.0, v33
	v_fma_f32 v35, -v34, v34, 1.0
	v_rcp_f32_e32 v33, v33
	v_sqrt_f32_e32 v35, v35
	v_add_f32_e32 v32, 1.0, v32
	v_rcp_f32_e32 v32, v32
	s_waitcnt lgkmcnt(13)
	v_lshlrev_b32_e32 v36, 16, v147
	v_mul_f32_e32 v33, v35, v33
	v_mul_f32_e32 v236, v33, v36
	v_mul_f32_e32 v32, v159, v32
	v_fmac_f32_e32 v236, v34, v235
	v_exp_f32_e32 v33, v58
	v_mul_f32_e32 v58, v34, v57
	v_exp_f32_e32 v32, v32
	v_exp_f32_e32 v34, v43
	v_add_f32_e32 v33, 1.0, v33
	v_rcp_f32_e32 v33, v33
	v_fma_f32 v35, -v32, v32, 1.0
	v_add_f32_e32 v34, 1.0, v34
	v_sqrt_f32_e32 v35, v35
	v_rcp_f32_e32 v34, v34
	s_waitcnt lgkmcnt(11)
	v_lshlrev_b32_e32 v36, 16, v148
	v_mul_f32_e32 v33, v35, v33
	v_mul_f32_e32 v34, v159, v34
	v_mul_f32_e32 v237, v33, v36
	v_exp_f32_e32 v33, v59
	v_exp_f32_e32 v34, v34
	v_fmac_f32_e32 v237, v32, v236
	v_mul_f32_e32 v59, v32, v58
	v_exp_f32_e32 v32, v44
	v_add_f32_e32 v33, 1.0, v33
	v_fma_f32 v35, -v34, v34, 1.0
	v_rcp_f32_e32 v33, v33
	v_sqrt_f32_e32 v35, v35
	v_add_f32_e32 v32, 1.0, v32
	v_rcp_f32_e32 v32, v32
	s_waitcnt lgkmcnt(9)
	v_lshlrev_b32_e32 v36, 16, v149
	v_mul_f32_e32 v33, v35, v33
	v_mul_f32_e32 v238, v33, v36
	v_mul_f32_e32 v32, v159, v32
	v_fmac_f32_e32 v238, v34, v237
	v_exp_f32_e32 v33, v60
	v_mul_f32_e32 v60, v34, v59
	v_exp_f32_e32 v32, v32
	v_exp_f32_e32 v34, v45
	v_add_f32_e32 v33, 1.0, v33
	v_rcp_f32_e32 v33, v33
	v_fma_f32 v35, -v32, v32, 1.0
	v_add_f32_e32 v34, 1.0, v34
	v_sqrt_f32_e32 v35, v35
	v_rcp_f32_e32 v34, v34
	s_waitcnt lgkmcnt(7)
	v_lshlrev_b32_e32 v36, 16, v239
	v_mul_f32_e32 v33, v35, v33
	v_mul_f32_e32 v34, v159, v34
	v_mul_f32_e32 v239, v33, v36
	v_exp_f32_e32 v33, v61
	v_exp_f32_e32 v34, v34
	v_fmac_f32_e32 v239, v32, v238
	v_mul_f32_e32 v61, v32, v60
	v_exp_f32_e32 v32, v46
	v_add_f32_e32 v33, 1.0, v33
	v_fma_f32 v35, -v34, v34, 1.0
	v_rcp_f32_e32 v33, v33
	v_sqrt_f32_e32 v35, v35
	v_add_f32_e32 v32, 1.0, v32
	v_rcp_f32_e32 v32, v32
	s_waitcnt lgkmcnt(5)
	v_lshlrev_b32_e32 v36, 16, v240
	v_mul_f32_e32 v33, v35, v33
	v_mul_f32_e32 v240, v33, v36
	v_fmac_f32_e32 v240, v34, v239
	v_exp_f32_e32 v33, v62
	v_mul_f32_e32 v62, v34, v61
	v_mul_f32_e32 v32, v159, v32
	v_exp_f32_e32 v34, v47
	v_exp_f32_e32 v32, v32
	v_add_f32_e32 v33, 1.0, v33
	v_rcp_f32_e32 v33, v33
	v_add_f32_e32 v34, 1.0, v34
	v_fma_f32 v35, -v32, v32, 1.0
	v_rcp_f32_e32 v34, v34
	v_sqrt_f32_e32 v35, v35
	s_waitcnt lgkmcnt(3)
	v_lshlrev_b32_e32 v36, 16, v241
	v_mul_f32_e32 v243, v32, v62
	v_mul_f32_e32 v34, v159, v34
	v_mul_f32_e32 v33, v35, v33
	v_exp_f32_e32 v35, v63
	v_exp_f32_e32 v34, v34
	v_mul_f32_e32 v63, v33, v36
	v_fmac_f32_e32 v63, v32, v240
	v_add_f32_e32 v33, 1.0, v35
	v_fma_f32 v35, -v34, v34, 1.0
	v_rcp_f32_e32 v33, v33
	v_sqrt_f32_e32 v35, v35
	s_waitcnt lgkmcnt(1)
	v_lshlrev_b32_e32 v32, 16, v242
	v_mul_f32_e32 v242, v34, v243
	ds_bpermute_b32 v244, v157, v242
	v_mul_f32_e32 v33, v35, v33
	v_mul_f32_e32 v241, v33, v32
	v_fmac_f32_e32 v241, v34, v63
	ds_bpermute_b32 v245, v157, v241
	s_and_saveexec_b64 s[18:19], vcc
	s_cbranch_execz .LBB0_313
	s_waitcnt lgkmcnt(0)
	v_fma_f32 v32, v244, v241, v245
	v_mul_f32_e32 v33, v242, v244
	v_add_u32_e32 v35, s98, v254
	ds_write2_b32 v35, v33, v32 offset1:32
; #define LAS __attribute__((address_space(3)))
; __device__ __forceinline__ unsigned cvt_pk_bf16(float lo, float hi) { unsigned r; asm volatile("v_cvt_pk_bf16_f32 %0, %1, %2" : "=v"(r) : "v"(lo), "v"(hi)); return r; }
; __device__ __forceinline__ float bf_lo(unsigned u) { return __uint_as_float(u << 16); }
; __device__ __forceinline__ float bf_hi(unsigned u) { return __uint_as_float(u & 0xffff0000u); }
; __device__ __forceinline__ bf16_t f2bf(float f) { return (bf16_t)(cvt_pk_bf16(f, 0.f) & 0xffffu); }
; #define LDS_BARRIER() do { asm volatile("s_waitcnt lgkmcnt(0)" ::: "memory"); __builtin_amdgcn_s_barrier(); asm volatile("" ::: "memory"); } while (0)
; template <int dir>
; __device__ __forceinline__ void lru_pass(LAS unsigned char* lds, const Params& P, int b, int h, int q, bool dry) {
;     ...
;             LDS_BARRIER();
;             float cin = carry, cend = carry;
; #pragma unroll
;             for (int w = 0; w < 8; ++w) { const float pw = AGG[(w * 2 + 0) * 32 + nl], ew = AGG[(w * 2 + 1) * 32 + nl]; if (w == wid) cin = cend; cend = fmaf(pw, cend, ew); }
;             carry = cend;
;             if (g) cin = fmaf(P0, cin, E0);
;             if (!isctx) {
; #pragma unroll
;                 for (int v = 0; v < 16; ++v) { const float hv = fmaf(zi[v], cin, zr[v]);
;                     const int s = sbase + v; const int tl = dir == 0 ? s : 255 - s;
;                     if (dir == 0) *(LAS unsigned*)(TOUT + tl * IO_WP + nl * 4) = (cvt_pk_bf16(hv, 0.f) & 0xffffu) | (pk[v] << 16);
;                     else *(LAS bf16_t*)(TOUT + tl * IO_NP + nl * 2) = f2bf((bf_lo(pk[v]) + hv) * bf_hi(pk[v])); }
;             }
;             t0_prev = t0;
;             cur = nxt;
;         }
.LBB0_313:
	s_or_b64 exec, exec, s[18:19]
	s_waitcnt lgkmcnt(0)
	s_barrier
	v_add_u32_e32 v34, s99, v161
	ds_read2_b32 v[36:37], v34 offset1:32
	ds_read2_b32 v[38:39], v34 offset0:64 offset1:96
	ds_read2_b32 v[40:41], v34 offset0:128 offset1:160
	ds_read2_b32 v[42:43], v34 offset0:192 offset1:224
	v_add_u32_e32 v32, s100, v161
	s_waitcnt lgkmcnt(3)
	v_fmac_f32_e32 v37, v36, v222
	s_waitcnt lgkmcnt(2)
	v_fmac_f32_e32 v39, v38, v37
	s_waitcnt lgkmcnt(1)
	v_fmac_f32_e32 v41, v40, v39
	ds_read2_b32 v[44:45], v32 offset1:32
	ds_read2_b32 v[46:47], v32 offset0:64 offset1:96
	ds_read2_b32 v[34:35], v32 offset0:128 offset1:160
	ds_read2_b32 v[32:33], v32 offset0:192 offset1:224
	s_waitcnt lgkmcnt(4)
	v_fmac_f32_e32 v43, v42, v41
	s_waitcnt lgkmcnt(3)
	v_fmac_f32_e32 v45, v44, v43
	s_waitcnt lgkmcnt(2)
	v_fmac_f32_e32 v47, v46, v45
	s_cmp_eq_u32 s44, 0
	s_waitcnt lgkmcnt(1)
	v_fmac_f32_e32 v35, v34, v47
	s_cbranch_scc1 .LBB0_315
	v_cndmask_b32_e64 v37, v222, v37, s[14:15]
	v_cndmask_b32_e64 v37, v37, v39, s[12:13]
	v_cndmask_b32_e64 v37, v37, v41, s[10:11]
	v_cndmask_b32_e64 v37, v37, v43, s[8:9]
	v_cndmask_b32_e64 v37, v37, v45, s[4:5]
	v_cndmask_b32_e64 v37, v37, v47, s[16:17]
	v_cndmask_b32_e32 v34, v244, v242, vcc
	v_cndmask_b32_e32 v36, v245, v241, vcc
	v_cndmask_b32_e64 v37, v37, v35, s[0:1]
	v_fmac_f32_e32 v36, v34, v37
	v_cndmask_b32_e32 v34, v36, v37, vcc
	v_fmac_f32_e32 v49, v227, v34
	v_lshlrev_b32_e32 v36, 16, v226
	v_add_f32_e32 v36, v49, v36
	v_and_b32_e32 v37, 0xffff0000, v226
	v_mul_f32_e32 v36, v36, v37
	v_cvt_pk_bf16_f32 v36, v36, v65
	ds_write_b16 v206, v36
	v_fmac_f32_e32 v228, v50, v34
	v_lshlrev_b32_e32 v36, 16, v225
	v_add_f32_e32 v36, v228, v36
	v_and_b32_e32 v37, 0xffff0000, v225
	v_mul_f32_e32 v36, v36, v37
	v_cvt_pk_bf16_f32 v36, v36, v65
	ds_write_b16 v207, v36
	v_fmac_f32_e32 v229, v51, v34
	v_lshlrev_b32_e32 v36, 16, v224
	v_add_f32_e32 v36, v229, v36
	v_and_b32_e32 v37, 0xffff0000, v224
	v_mul_f32_e32 v36, v36, v37
	v_cvt_pk_bf16_f32 v36, v36, v65
	ds_write_b16 v208, v36
	v_fmac_f32_e32 v230, v52, v34
	v_lshlrev_b32_e32 v36, 16, v223
	v_add_f32_e32 v36, v230, v36
	v_and_b32_e32 v37, 0xffff0000, v223
	v_mul_f32_e32 v36, v36, v37
	v_cvt_pk_bf16_f32 v36, v36, v65
	ds_write_b16 v209, v36
	v_fmac_f32_e32 v231, v53, v34
	v_lshlrev_b32_e32 v36, 16, v135
	v_add_f32_e32 v36, v231, v36
	v_and_b32_e32 v37, 0xffff0000, v135
	v_mul_f32_e32 v36, v36, v37
	v_cvt_pk_bf16_f32 v36, v36, v65
	ds_write_b16 v210, v36
	v_fmac_f32_e32 v232, v54, v34
	v_lshlrev_b32_e32 v36, 16, v134
	v_add_f32_e32 v36, v232, v36
	v_and_b32_e32 v37, 0xffff0000, v134
	v_mul_f32_e32 v36, v36, v37
	v_cvt_pk_bf16_f32 v36, v36, v65
	ds_write_b16 v211, v36
	v_fmac_f32_e32 v233, v55, v34
	v_lshlrev_b32_e32 v36, 16, v133
	v_add_f32_e32 v36, v233, v36
	v_and_b32_e32 v37, 0xffff0000, v133
	v_mul_f32_e32 v36, v36, v37
	v_cvt_pk_bf16_f32 v36, v36, v65
	ds_write_b16 v212, v36
	v_fmac_f32_e32 v234, v56, v34
	v_lshlrev_b32_e32 v36, 16, v131
	v_add_f32_e32 v36, v234, v36
	v_and_b32_e32 v37, 0xffff0000, v131
	v_mul_f32_e32 v36, v36, v37
	v_cvt_pk_bf16_f32 v36, v36, v65
	ds_write_b16 v213, v36
	v_fmac_f32_e32 v235, v57, v34
	v_lshlrev_b32_e32 v36, 16, v132
	v_add_f32_e32 v36, v235, v36
	v_and_b32_e32 v37, 0xffff0000, v132
	v_mul_f32_e32 v36, v36, v37
	v_cvt_pk_bf16_f32 v36, v36, v65
	ds_write_b16 v214, v36
	v_fmac_f32_e32 v236, v58, v34
	v_lshlrev_b32_e32 v36, 16, v130
	v_add_f32_e32 v36, v236, v36
	v_and_b32_e32 v37, 0xffff0000, v130
	v_mul_f32_e32 v36, v36, v37
	v_cvt_pk_bf16_f32 v36, v36, v65
	ds_write_b16 v215, v36
	v_fmac_f32_e32 v237, v59, v34
	v_lshlrev_b32_e32 v36, 16, v129
	v_add_f32_e32 v36, v237, v36
	v_and_b32_e32 v37, 0xffff0000, v129
	v_mul_f32_e32 v36, v36, v37
	v_cvt_pk_bf16_f32 v36, v36, v65
	ds_write_b16 v216, v36
	v_fmac_f32_e32 v238, v60, v34
	v_lshlrev_b32_e32 v36, 16, v128
	v_add_f32_e32 v36, v238, v36
	v_and_b32_e32 v37, 0xffff0000, v128
	v_mul_f32_e32 v36, v36, v37
	v_cvt_pk_bf16_f32 v36, v36, v65
	ds_write_b16 v217, v36
	v_fmac_f32_e32 v239, v61, v34
	v_lshlrev_b32_e32 v36, 16, v67
	v_add_f32_e32 v36, v239, v36
	v_and_b32_e32 v37, 0xffff0000, v67
	v_mul_f32_e32 v36, v36, v37
	v_cvt_pk_bf16_f32 v36, v36, v65
	ds_write_b16 v218, v36
	v_fmac_f32_e32 v240, v62, v34
	v_lshlrev_b32_e32 v36, 16, v66
	v_add_f32_e32 v36, v240, v36
	v_and_b32_e32 v37, 0xffff0000, v66
	v_mul_f32_e32 v36, v36, v37
	v_cvt_pk_bf16_f32 v36, v36, v65
	ds_write_b16 v219, v36
	v_fmac_f32_e32 v63, v243, v34
	v_lshlrev_b32_e32 v36, 16, v64
	v_add_f32_e32 v36, v63, v36
	v_and_b32_e32 v37, 0xffff0000, v64
	v_mul_f32_e32 v36, v36, v37
	v_cvt_pk_bf16_f32 v36, v36, v65
	v_fmac_f32_e32 v241, v242, v34
	v_lshlrev_b32_e32 v34, 16, v48
	ds_write_b16 v220, v36
	v_add_f32_e32 v34, v241, v34
	v_and_b32_e32 v36, 0xffff0000, v48
	v_mul_f32_e32 v34, v34, v36
	v_cvt_pk_bf16_f32 v34, v34, v65
	ds_write_b16 v221, v34
.LBB0_315:
	s_xor_b32 s98, s98, 0x14000
	s_xor_b32 s99, s99, 0x14000
	s_xor_b32 s100, s100, 0x14000
	s_add_i32 s46, s46, 1
	s_add_u32 s44, s44, 0xfff00000
	s_mov_b32 s6, 0xffff0000
	s_addc_u32 s45, s45, -1
	s_addk_i32 s25, 0xff00
	s_mov_b32 s7, -1
	s_waitcnt lgkmcnt(0)
	v_fmac_f32_e32 v33, v32, v35
	s_cmp_lg_u32 s46, 9
	v_lshl_add_u64 v[144:145], v[144:145], 0, s[6:7]
	s_cbranch_scc0 .LBB0_277
	v_mov_b32_e32 v222, v33
	s_mov_b32 s78, s29
	s_mov_b32 s29, s20
	s_branch .LBB0_306
